# K-loops: per-section s_setprio flips removed (A/B)
# speedup vs baseline: 1.0112x; 1.0112x over previous
.LBB0_138:
	s_add_u32 s6, s0, 0xfff80080
	s_addc_u32 s7, s1, -1
	s_add_i32 s76, 0, 0x10000
	ds_read_b128 v[130:133], v224
	ds_read_b128 v[134:137], v224 offset:1024
	ds_read_b128 v[138:141], v224 offset:2048
	ds_read_b128 v[142:145], v224 offset:3072
	s_cmp_eq_u32 s49, 28
	s_cselect_b32 s13, s51, s7
	s_cselect_b32 s12, s50, s6
	s_cselect_b32 s7, s22, s39
	s_cselect_b32 s6, s23, s38
	s_add_i32 m0, s31, 0xc000
	ds_read_b128 v[152:155], v174
	ds_read_b128 v[166:169], v174 offset:1024
	ds_read_b128 v[170:173], v174 offset:2048
	ds_read_b128 v[176:179], v174 offset:3072
	ds_read_b128 v[180:183], v174 offset:4096
	ds_read_b128 v[184:187], v174 offset:5120
	ds_read_b128 v[188:191], v174 offset:6144
	global_load_lds_dwordx4 v162, s[0:1]
	s_add_i32 m0, s31, 0xe000
	ds_read_b128 v[192:195], v174 offset:7168
	global_load_lds_dwordx4 v164, s[0:1]
	s_waitcnt lgkmcnt(8)
	s_barrier
	s_waitcnt lgkmcnt(7)
	v_mfma_f32_16x16x32_bf16 v[126:129], v[130:133], v[152:155], v[126:129]
	v_mfma_f32_16x16x32_bf16 v[122:125], v[138:141], v[152:155], v[122:125]
	s_waitcnt lgkmcnt(5)
	v_mfma_f32_16x16x32_bf16 v[114:117], v[130:133], v[170:173], v[114:117]
	v_mfma_f32_16x16x32_bf16 v[106:109], v[138:141], v[170:173], v[106:109]
	s_waitcnt lgkmcnt(3)
	v_mfma_f32_16x16x32_bf16 v[98:101], v[130:133], v[180:183], v[98:101]
	v_mfma_f32_16x16x32_bf16 v[90:93], v[138:141], v[180:183], v[90:93]
	s_waitcnt lgkmcnt(1)
	v_mfma_f32_16x16x32_bf16 v[82:85], v[130:133], v[188:191], v[82:85]
	v_mfma_f32_16x16x32_bf16 v[74:77], v[138:141], v[188:191], v[74:77]
	v_mfma_f32_16x16x32_bf16 v[126:129], v[134:137], v[166:169], v[126:129]
	v_mfma_f32_16x16x32_bf16 v[122:125], v[142:145], v[166:169], v[122:125]
	v_mfma_f32_16x16x32_bf16 v[114:117], v[134:137], v[176:179], v[114:117]
	v_mfma_f32_16x16x32_bf16 v[106:109], v[142:145], v[176:179], v[106:109]
	v_mfma_f32_16x16x32_bf16 v[98:101], v[134:137], v[184:187], v[98:101]
	v_mfma_f32_16x16x32_bf16 v[90:93], v[142:145], v[184:187], v[90:93]
	s_waitcnt lgkmcnt(0)
	v_mfma_f32_16x16x32_bf16 v[82:85], v[134:137], v[192:195], v[82:85]
	v_mfma_f32_16x16x32_bf16 v[74:77], v[142:145], v[192:195], v[74:77]
	s_barrier
	s_add_i32 s78, 0, 0x14000
	s_add_i32 s76, s76, s30
	s_mov_b32 m0, s76
	ds_read_b128 v[196:199], v225
	ds_read_b128 v[200:203], v225 offset:1024
	ds_read_b128 v[204:207], v225 offset:2048
	global_load_lds_dwordx4 v158, s[6:7]
	s_add_i32 m0, s76, 0x2000
	ds_read_b128 v[216:219], v225 offset:3072
	global_load_lds_dwordx4 v146, s[6:7]
	s_barrier
	s_waitcnt lgkmcnt(3)
	v_mfma_f32_16x16x32_bf16 v[118:121], v[196:199], v[152:155], v[118:121]
	s_waitcnt lgkmcnt(1)
	v_mfma_f32_16x16x32_bf16 v[110:113], v[204:207], v[152:155], v[110:113]
	v_mfma_f32_16x16x32_bf16 v[102:105], v[196:199], v[170:173], v[102:105]
	v_mfma_f32_16x16x32_bf16 v[94:97], v[204:207], v[170:173], v[94:97]
	v_mfma_f32_16x16x32_bf16 v[86:89], v[196:199], v[180:183], v[86:89]
	v_mfma_f32_16x16x32_bf16 v[78:81], v[204:207], v[180:183], v[78:81]
	v_mfma_f32_16x16x32_bf16 v[70:73], v[196:199], v[188:191], v[70:73]
	v_mfma_f32_16x16x32_bf16 v[66:69], v[204:207], v[188:191], v[66:69]
	v_mfma_f32_16x16x32_bf16 v[118:121], v[200:203], v[166:169], v[118:121]
	s_waitcnt lgkmcnt(0)
	v_mfma_f32_16x16x32_bf16 v[110:113], v[216:219], v[166:169], v[110:113]
	v_mfma_f32_16x16x32_bf16 v[102:105], v[200:203], v[176:179], v[102:105]
	v_mfma_f32_16x16x32_bf16 v[94:97], v[216:219], v[176:179], v[94:97]
	v_mfma_f32_16x16x32_bf16 v[86:89], v[200:203], v[184:187], v[86:89]
	v_mfma_f32_16x16x32_bf16 v[78:81], v[216:219], v[184:187], v[78:81]
	v_mfma_f32_16x16x32_bf16 v[70:73], v[200:203], v[192:195], v[70:73]
	v_mfma_f32_16x16x32_bf16 v[66:69], v[216:219], v[192:195], v[66:69]
	s_mov_b32 m0, s31
	s_add_u32 s98, s12, 0x80
	s_addc_u32 s99, s13, 0
	s_barrier
	ds_read_b128 v[152:155], v174 offset:16384
	ds_read_b128 v[166:169], v174 offset:17408
	ds_read_b128 v[170:173], v174 offset:18432
	ds_read_b128 v[176:179], v174 offset:19456
	ds_read_b128 v[180:183], v174 offset:20480
	ds_read_b128 v[184:187], v174 offset:21504
	ds_read_b128 v[188:191], v174 offset:22528
	global_load_lds_dwordx4 v160, s[12:13]
	s_mov_b32 m0, s40
	ds_read_b128 v[192:195], v174 offset:23552
	global_load_lds_dwordx4 v156, s[12:13]
	s_barrier
	s_waitcnt lgkmcnt(7)
	v_mfma_f32_16x16x32_bf16 v[62:65], v[130:133], v[152:155], v[62:65]
	v_mfma_f32_16x16x32_bf16 v[58:61], v[138:141], v[152:155], v[58:61]
	s_waitcnt lgkmcnt(5)
	v_mfma_f32_16x16x32_bf16 v[50:53], v[130:133], v[170:173], v[50:53]
	v_mfma_f32_16x16x32_bf16 v[42:45], v[138:141], v[170:173], v[42:45]
	s_waitcnt lgkmcnt(3)
	v_mfma_f32_16x16x32_bf16 v[34:37], v[130:133], v[180:183], v[34:37]
	v_mfma_f32_16x16x32_bf16 v[26:29], v[138:141], v[180:183], v[26:29]
	s_waitcnt lgkmcnt(1)
	v_mfma_f32_16x16x32_bf16 v[18:21], v[130:133], v[188:191], v[18:21]
	v_mfma_f32_16x16x32_bf16 v[10:13], v[138:141], v[188:191], v[10:13]
	v_mfma_f32_16x16x32_bf16 v[62:65], v[134:137], v[166:169], v[62:65]
	v_mfma_f32_16x16x32_bf16 v[58:61], v[142:145], v[166:169], v[58:61]
	v_mfma_f32_16x16x32_bf16 v[50:53], v[134:137], v[176:179], v[50:53]
	v_mfma_f32_16x16x32_bf16 v[42:45], v[142:145], v[176:179], v[42:45]
	v_mfma_f32_16x16x32_bf16 v[34:37], v[134:137], v[184:187], v[34:37]
	v_mfma_f32_16x16x32_bf16 v[26:29], v[142:145], v[184:187], v[26:29]
	s_waitcnt lgkmcnt(0)
	v_mfma_f32_16x16x32_bf16 v[18:21], v[134:137], v[192:195], v[18:21]
	v_mfma_f32_16x16x32_bf16 v[10:13], v[142:145], v[192:195], v[10:13]
	s_barrier
	s_add_i32 s78, s78, s30
	s_mov_b32 m0, s78
	s_add_u32 s76, s6, 0x80000
	s_addc_u32 s77, s7, 0
	global_load_lds_dwordx4 v158, s[76:77]
	s_add_i32 m0, s78, 0x2000
	s_nop 0
	global_load_lds_dwordx4 v146, s[76:77]
	s_waitcnt vmcnt(6)
	s_barrier
	v_mfma_f32_16x16x32_bf16 v[54:57], v[196:199], v[152:155], v[54:57]
	v_mfma_f32_16x16x32_bf16 v[46:49], v[204:207], v[152:155], v[46:49]
	v_mfma_f32_16x16x32_bf16 v[38:41], v[196:199], v[170:173], v[38:41]
	v_mfma_f32_16x16x32_bf16 v[30:33], v[204:207], v[170:173], v[30:33]
	v_mfma_f32_16x16x32_bf16 v[22:25], v[196:199], v[180:183], v[22:25]
	v_mfma_f32_16x16x32_bf16 v[14:17], v[204:207], v[180:183], v[14:17]
	v_mfma_f32_16x16x32_bf16 v[6:9], v[196:199], v[188:191], v[6:9]
	v_mfma_f32_16x16x32_bf16 v[2:5], v[204:207], v[188:191], v[2:5]
	v_mfma_f32_16x16x32_bf16 v[54:57], v[200:203], v[166:169], v[54:57]
	v_mfma_f32_16x16x32_bf16 v[46:49], v[216:219], v[166:169], v[46:49]
	v_mfma_f32_16x16x32_bf16 v[38:41], v[200:203], v[176:179], v[38:41]
	v_mfma_f32_16x16x32_bf16 v[30:33], v[216:219], v[176:179], v[30:33]
	v_mfma_f32_16x16x32_bf16 v[22:25], v[200:203], v[184:187], v[22:25]
	v_mfma_f32_16x16x32_bf16 v[14:17], v[216:219], v[184:187], v[14:17]
	v_mfma_f32_16x16x32_bf16 v[6:9], v[200:203], v[192:195], v[6:9]
	v_mfma_f32_16x16x32_bf16 v[2:5], v[216:219], v[192:195], v[2:5]
	s_add_i32 s76, 0, 0x18000
	s_barrier
	ds_read_b128 v[130:133], v226
	ds_read_b128 v[134:137], v226 offset:1024
	ds_read_b128 v[138:141], v226 offset:2048
	ds_read_b128 v[142:145], v226 offset:3072
	s_add_u32 s12, s12, 0x80000
	s_addc_u32 s13, s13, 0
	s_mov_b32 m0, s41
	ds_read_b128 v[152:155], v174 offset:32768
	ds_read_b128 v[166:169], v174 offset:33792
	ds_read_b128 v[170:173], v174 offset:34816
	ds_read_b128 v[176:179], v174 offset:35840
	ds_read_b128 v[180:183], v174 offset:36864
	ds_read_b128 v[184:187], v174 offset:37888
	ds_read_b128 v[188:191], v174 offset:38912
	global_load_lds_dwordx4 v160, s[12:13]
	s_mov_b32 m0, s60
	ds_read_b128 v[192:195], v174 offset:39936
	global_load_lds_dwordx4 v156, s[12:13]
	s_waitcnt lgkmcnt(8)
	s_barrier
	s_waitcnt lgkmcnt(7)
	v_mfma_f32_16x16x32_bf16 v[126:129], v[130:133], v[152:155], v[126:129]
	v_mfma_f32_16x16x32_bf16 v[122:125], v[138:141], v[152:155], v[122:125]
	s_waitcnt lgkmcnt(5)
	v_mfma_f32_16x16x32_bf16 v[114:117], v[130:133], v[170:173], v[114:117]
	v_mfma_f32_16x16x32_bf16 v[106:109], v[138:141], v[170:173], v[106:109]
	s_waitcnt lgkmcnt(3)
	v_mfma_f32_16x16x32_bf16 v[98:101], v[130:133], v[180:183], v[98:101]
	v_mfma_f32_16x16x32_bf16 v[90:93], v[138:141], v[180:183], v[90:93]
	s_waitcnt lgkmcnt(1)
	v_mfma_f32_16x16x32_bf16 v[82:85], v[130:133], v[188:191], v[82:85]
	v_mfma_f32_16x16x32_bf16 v[74:77], v[138:141], v[188:191], v[74:77]
	v_mfma_f32_16x16x32_bf16 v[126:129], v[134:137], v[166:169], v[126:129]
	v_mfma_f32_16x16x32_bf16 v[122:125], v[142:145], v[166:169], v[122:125]
	v_mfma_f32_16x16x32_bf16 v[114:117], v[134:137], v[176:179], v[114:117]
	v_mfma_f32_16x16x32_bf16 v[106:109], v[142:145], v[176:179], v[106:109]
	v_mfma_f32_16x16x32_bf16 v[98:101], v[134:137], v[184:187], v[98:101]
	v_mfma_f32_16x16x32_bf16 v[90:93], v[142:145], v[184:187], v[90:93]
	s_waitcnt lgkmcnt(0)
	v_mfma_f32_16x16x32_bf16 v[82:85], v[134:137], v[192:195], v[82:85]
	v_mfma_f32_16x16x32_bf16 v[74:77], v[142:145], v[192:195], v[74:77]
	s_barrier
	s_add_i32 s12, 0, 0x1c000
	s_add_i32 s13, s76, s30
	s_add_u32 s100, s6, 0x80
	s_addc_u32 s101, s7, 0
	s_mov_b32 m0, s13
	ds_read_b128 v[196:199], v227
	ds_read_b128 v[200:203], v227 offset:1024
	ds_read_b128 v[204:207], v227 offset:2048
	global_load_lds_dwordx4 v158, s[100:101]
	s_add_i32 m0, s13, 0x2000
	ds_read_b128 v[216:219], v227 offset:3072
	global_load_lds_dwordx4 v146, s[100:101]
	s_barrier
	s_waitcnt lgkmcnt(3)
	v_mfma_f32_16x16x32_bf16 v[118:121], v[196:199], v[152:155], v[118:121]
	s_waitcnt lgkmcnt(1)
	v_mfma_f32_16x16x32_bf16 v[110:113], v[204:207], v[152:155], v[110:113]
	v_mfma_f32_16x16x32_bf16 v[102:105], v[196:199], v[170:173], v[102:105]
	v_mfma_f32_16x16x32_bf16 v[94:97], v[204:207], v[170:173], v[94:97]
	v_mfma_f32_16x16x32_bf16 v[86:89], v[196:199], v[180:183], v[86:89]
	v_mfma_f32_16x16x32_bf16 v[78:81], v[204:207], v[180:183], v[78:81]
	v_mfma_f32_16x16x32_bf16 v[70:73], v[196:199], v[188:191], v[70:73]
	v_mfma_f32_16x16x32_bf16 v[66:69], v[204:207], v[188:191], v[66:69]
	v_mfma_f32_16x16x32_bf16 v[118:121], v[200:203], v[166:169], v[118:121]
	s_waitcnt lgkmcnt(0)
	v_mfma_f32_16x16x32_bf16 v[110:113], v[216:219], v[166:169], v[110:113]
	v_mfma_f32_16x16x32_bf16 v[102:105], v[200:203], v[176:179], v[102:105]
	v_mfma_f32_16x16x32_bf16 v[94:97], v[216:219], v[176:179], v[94:97]
	v_mfma_f32_16x16x32_bf16 v[86:89], v[200:203], v[184:187], v[86:89]
	v_mfma_f32_16x16x32_bf16 v[78:81], v[216:219], v[184:187], v[78:81]
	v_mfma_f32_16x16x32_bf16 v[70:73], v[200:203], v[192:195], v[70:73]
	v_mfma_f32_16x16x32_bf16 v[66:69], v[216:219], v[192:195], v[66:69]
	s_mov_b32 m0, s64
	s_barrier
	ds_read_b128 v[152:155], v174 offset:49152
	ds_read_b128 v[166:169], v174 offset:50176
	ds_read_b128 v[170:173], v174 offset:51200
	ds_read_b128 v[176:179], v174 offset:52224
	ds_read_b128 v[180:183], v174 offset:53248
	ds_read_b128 v[184:187], v174 offset:54272
	ds_read_b128 v[188:191], v174 offset:55296
	global_load_lds_dwordx4 v160, s[98:99]
	s_mov_b32 m0, s65
	ds_read_b128 v[192:195], v174 offset:56320
	global_load_lds_dwordx4 v156, s[98:99]
	s_barrier
	s_waitcnt lgkmcnt(7)
	v_mfma_f32_16x16x32_bf16 v[62:65], v[130:133], v[152:155], v[62:65]
	v_mfma_f32_16x16x32_bf16 v[58:61], v[138:141], v[152:155], v[58:61]
	s_waitcnt lgkmcnt(5)
	v_mfma_f32_16x16x32_bf16 v[50:53], v[130:133], v[170:173], v[50:53]
	v_mfma_f32_16x16x32_bf16 v[42:45], v[138:141], v[170:173], v[42:45]
	s_waitcnt lgkmcnt(3)
	v_mfma_f32_16x16x32_bf16 v[34:37], v[130:133], v[180:183], v[34:37]
	v_mfma_f32_16x16x32_bf16 v[26:29], v[138:141], v[180:183], v[26:29]
	s_waitcnt lgkmcnt(1)
	v_mfma_f32_16x16x32_bf16 v[18:21], v[130:133], v[188:191], v[18:21]
	v_mfma_f32_16x16x32_bf16 v[10:13], v[138:141], v[188:191], v[10:13]
	v_mfma_f32_16x16x32_bf16 v[62:65], v[134:137], v[166:169], v[62:65]
	v_mfma_f32_16x16x32_bf16 v[58:61], v[142:145], v[166:169], v[58:61]
	v_mfma_f32_16x16x32_bf16 v[50:53], v[134:137], v[176:179], v[50:53]
	v_mfma_f32_16x16x32_bf16 v[42:45], v[142:145], v[176:179], v[42:45]
	v_mfma_f32_16x16x32_bf16 v[34:37], v[134:137], v[184:187], v[34:37]
	v_mfma_f32_16x16x32_bf16 v[26:29], v[142:145], v[184:187], v[26:29]
	s_waitcnt lgkmcnt(0)
	v_mfma_f32_16x16x32_bf16 v[18:21], v[134:137], v[192:195], v[18:21]
	v_mfma_f32_16x16x32_bf16 v[10:13], v[142:145], v[192:195], v[10:13]
	s_barrier
	s_add_i32 s12, s12, s30
	s_mov_b32 m0, s12
	s_add_u32 s6, s6, 0x80080
	s_addc_u32 s7, s7, 0
	global_load_lds_dwordx4 v158, s[6:7]
	s_add_i32 m0, s12, 0x2000
	s_nop 0
	global_load_lds_dwordx4 v146, s[6:7]
	s_waitcnt vmcnt(6)
	s_barrier
	v_mfma_f32_16x16x32_bf16 v[54:57], v[196:199], v[152:155], v[54:57]
	v_mfma_f32_16x16x32_bf16 v[46:49], v[204:207], v[152:155], v[46:49]
	v_mfma_f32_16x16x32_bf16 v[38:41], v[196:199], v[170:173], v[38:41]
	v_mfma_f32_16x16x32_bf16 v[30:33], v[204:207], v[170:173], v[30:33]
	v_mfma_f32_16x16x32_bf16 v[22:25], v[196:199], v[180:183], v[22:25]
	v_mfma_f32_16x16x32_bf16 v[14:17], v[204:207], v[180:183], v[14:17]
	v_mfma_f32_16x16x32_bf16 v[6:9], v[196:199], v[188:191], v[6:9]
	v_mfma_f32_16x16x32_bf16 v[2:5], v[204:207], v[188:191], v[2:5]
	v_mfma_f32_16x16x32_bf16 v[54:57], v[200:203], v[166:169], v[54:57]
	v_mfma_f32_16x16x32_bf16 v[46:49], v[216:219], v[166:169], v[46:49]
	v_mfma_f32_16x16x32_bf16 v[38:41], v[200:203], v[176:179], v[38:41]
	v_mfma_f32_16x16x32_bf16 v[30:33], v[216:219], v[176:179], v[30:33]
	v_mfma_f32_16x16x32_bf16 v[22:25], v[200:203], v[184:187], v[22:25]
	v_mfma_f32_16x16x32_bf16 v[14:17], v[216:219], v[184:187], v[14:17]
	v_mfma_f32_16x16x32_bf16 v[6:9], v[200:203], v[192:195], v[6:9]
	v_mfma_f32_16x16x32_bf16 v[2:5], v[216:219], v[192:195], v[2:5]
	s_add_i32 s49, s49, 2
	s_add_u32 s0, s0, 0x100
	s_addc_u32 s1, s1, 0
	s_add_u32 s38, s38, 0x100
	s_addc_u32 s39, s39, 0
	s_cmp_gt_u32 s49, 29
	s_barrier
	s_cbranch_scc0 .LBB0_138
	v_mov_b32_e32 v0, v148
	s_cmp_gt_i32 s69, 15
	v_and_b32_e32 v176, 15, v0
	v_bfe_u32 v175, v0, 4, 2
	s_mov_b64 s[0:1], -1
	s_cbranch_scc0 .LBB0_157
	s_cmp_gt_u32 s69, 23
	s_cbranch_scc0 .LBB0_154
	s_cmp_gt_u32 s69, 31
	s_cbranch_scc0 .LBB0_151
	s_cmp_gt_u32 s69, 39
	s_cbranch_scc0 .LBB0_148
	v_mul_f32_e32 v0, 0xbfb8aa3b, v126
	v_exp_f32_e32 v131, v0
	s_lshr_b32 s0, s75, 3
	s_mulk_i32 s0, 0x880
	s_lshl_b32 s1, s75, 8
	v_add_f32_e32 v131, 1.0, v131
	v_rcp_f32_e32 v132, v131
	v_mul_f32_e32 v131, 0xbfb8aa3b, v122
	v_mul_f32_e32 v133, 0xbfb8aa3b, v127
	v_mul_f32_e32 v134, 0xbfb8aa3b, v123
	v_mul_f32_e32 v135, 0xbfb8aa3b, v128
	v_mul_f32_e32 v136, 0xbfb8aa3b, v124
	v_mul_f32_e32 v137, 0xbfb8aa3b, v129
	v_mul_f32_e32 v138, 0xbfb8aa3b, v125
	v_mul_f32_e32 v139, 0xbfb8aa3b, v118
	v_mul_f32_e32 v140, 0xbfb8aa3b, v110
	v_mul_f32_e32 v141, 0xbfb8aa3b, v119
	v_mul_f32_e32 v142, 0xbfb8aa3b, v111
	v_mul_f32_e32 v143, 0xbfb8aa3b, v120
	v_mul_f32_e32 v152, 0xbfb8aa3b, v112
	v_mul_f32_e32 v153, 0xbfb8aa3b, v121
	v_mul_f32_e32 v154, 0xbfb8aa3b, v113
	v_mul_f32_e32 v155, 0xbfb8aa3b, v114
	v_mul_f32_e32 v177, 0xbfb8aa3b, v106
	v_mul_f32_e32 v178, 0xbfb8aa3b, v115
	v_mul_f32_e32 v179, 0xbfb8aa3b, v107
	v_mul_f32_e32 v180, 0xbfb8aa3b, v116
	v_mul_f32_e32 v181, 0xbfb8aa3b, v108
	v_mul_f32_e32 v182, 0xbfb8aa3b, v117
	v_mul_f32_e32 v183, 0xbfb8aa3b, v109
	v_mul_f32_e32 v184, 0xbfb8aa3b, v102
	v_mul_f32_e32 v185, 0xbfb8aa3b, v94
	v_mul_f32_e32 v186, 0xbfb8aa3b, v103
	v_mul_f32_e32 v187, 0xbfb8aa3b, v95
	v_mul_f32_e32 v188, 0xbfb8aa3b, v104
	v_mul_f32_e32 v189, 0xbfb8aa3b, v96
	v_mul_f32_e32 v190, 0xbfb8aa3b, v105
	v_mul_f32_e32 v191, 0xbfb8aa3b, v97
	v_mul_f32_e32 v192, 0xbfb8aa3b, v98
	v_mul_f32_e32 v193, 0xbfb8aa3b, v90
	v_mul_f32_e32 v194, 0xbfb8aa3b, v99
	v_mul_f32_e32 v195, 0xbfb8aa3b, v91
	v_mul_f32_e32 v196, 0xbfb8aa3b, v100
	v_mul_f32_e32 v197, 0xbfb8aa3b, v92
	v_mul_f32_e32 v198, 0xbfb8aa3b, v101
	v_mul_f32_e32 v199, 0xbfb8aa3b, v93
	v_mul_f32_e32 v200, 0xbfb8aa3b, v86
	v_mul_f32_e32 v201, 0xbfb8aa3b, v78
	v_mul_f32_e32 v202, 0xbfb8aa3b, v87
	v_mul_f32_e32 v203, 0xbfb8aa3b, v79
	v_mul_f32_e32 v204, 0xbfb8aa3b, v88
	v_mul_f32_e32 v205, 0xbfb8aa3b, v80
	v_mul_f32_e32 v206, 0xbfb8aa3b, v89
	v_mul_f32_e32 v207, 0xbfb8aa3b, v81
	v_mul_f32_e32 v208, 0xbfb8aa3b, v82
	v_mul_f32_e32 v209, 0xbfb8aa3b, v74
	v_mul_f32_e32 v215, 0xbfb8aa3b, v83
	v_mul_f32_e32 v216, 0xbfb8aa3b, v75
	v_mul_f32_e32 v217, 0xbfb8aa3b, v84
	v_mul_f32_e32 v218, 0xbfb8aa3b, v76
	v_mul_f32_e32 v219, 0xbfb8aa3b, v85
	v_mul_f32_e32 v220, 0xbfb8aa3b, v77
	v_mul_f32_e32 v221, 0xbfb8aa3b, v70
	v_mul_f32_e32 v222, 0xbfb8aa3b, v66
	v_mul_f32_e32 v223, 0xbfb8aa3b, v71
	v_mul_f32_e32 v224, 0xbfb8aa3b, v67
	v_mul_f32_e32 v225, 0xbfb8aa3b, v72
	v_mul_f32_e32 v226, 0xbfb8aa3b, v68
	v_mul_f32_e32 v227, 0xbfb8aa3b, v73
	v_mul_f32_e32 v228, 0xbfb8aa3b, v69
	v_mul_f32_e32 v229, 0xbfb8aa3b, v62
	v_mul_f32_e32 v230, 0xbfb8aa3b, v58
	v_mul_f32_e32 v231, 0xbfb8aa3b, v63
	v_mul_f32_e32 v232, 0xbfb8aa3b, v59
	v_mul_f32_e32 v233, 0xbfb8aa3b, v64
	v_mul_f32_e32 v234, 0xbfb8aa3b, v60
	v_mul_f32_e32 v235, 0xbfb8aa3b, v65
	v_mul_f32_e32 v236, 0xbfb8aa3b, v61
	v_mul_f32_e32 v237, 0xbfb8aa3b, v54
	v_mul_f32_e32 v238, 0xbfb8aa3b, v46
	v_mul_f32_e32 v239, 0xbfb8aa3b, v55
	s_and_b32 s1, s1, 0x700
	s_add_i32 s0, s0, s66
	v_exp_f32_e32 v173, v131
	v_exp_f32_e32 v133, v133
	v_exp_f32_e32 v172, v134
	v_exp_f32_e32 v171, v135
	v_exp_f32_e32 v170, v136
	v_exp_f32_e32 v169, v137
	v_exp_f32_e32 v131, v138
	v_exp_f32_e32 v168, v139
	v_exp_f32_e32 v167, v140
	v_exp_f32_e32 v166, v141
	v_exp_f32_e32 v145, v142
	v_exp_f32_e32 v144, v143
	v_exp_f32_e32 v143, v152
	v_exp_f32_e32 v142, v153
	v_exp_f32_e32 v141, v154
	v_exp_f32_e32 v140, v155
	v_exp_f32_e32 v139, v177
	v_exp_f32_e32 v138, v178
	v_exp_f32_e32 v213, v179
	v_exp_f32_e32 v155, v180
	v_exp_f32_e32 v154, v181
	v_exp_f32_e32 v153, v182
	v_exp_f32_e32 v152, v183
	v_exp_f32_e32 v212, v184
	v_exp_f32_e32 v211, v185
	v_exp_f32_e32 v252, v186
	v_exp_f32_e32 v251, v187
	v_exp_f32_e32 v250, v188
	v_exp_f32_e32 v249, v189
	v_exp_f32_e32 v248, v190
	v_exp_f32_e32 v247, v191
	v_exp_f32_e32 v246, v192
	v_exp_f32_e32 v245, v193
	v_exp_f32_e32 v244, v194
	v_exp_f32_e32 v243, v195
	v_exp_f32_e32 v242, v196
	v_exp_f32_e32 v241, v197
	v_exp_f32_e32 v184, v198
	v_exp_f32_e32 v177, v199
	v_exp_f32_e32 v198, v200
	v_exp_f32_e32 v199, v201
	v_exp_f32_e32 v197, v202
	v_exp_f32_e32 v196, v203
	v_exp_f32_e32 v195, v204
	v_exp_f32_e32 v194, v205
	v_exp_f32_e32 v193, v206
	v_exp_f32_e32 v192, v207
	v_exp_f32_e32 v191, v208
	v_exp_f32_e32 v190, v209
	v_exp_f32_e32 v189, v215
	v_exp_f32_e32 v188, v216
	v_exp_f32_e32 v187, v217
	v_exp_f32_e32 v186, v218
	v_exp_f32_e32 v185, v219
	v_exp_f32_e32 v201, v220
	v_exp_f32_e32 v200, v221
	v_exp_f32_e32 v221, v222
	v_exp_f32_e32 v220, v223
	v_exp_f32_e32 v219, v224
	v_exp_f32_e32 v218, v225
	v_exp_f32_e32 v217, v226
	v_exp_f32_e32 v216, v227
	v_exp_f32_e32 v215, v228
	v_exp_f32_e32 v209, v229
	v_exp_f32_e32 v208, v230
	v_exp_f32_e32 v207, v231
	v_exp_f32_e32 v206, v232
	v_exp_f32_e32 v205, v233
	v_exp_f32_e32 v204, v234
	v_exp_f32_e32 v203, v235
	v_exp_f32_e32 v202, v236
	v_exp_f32_e32 v223, v237
	v_exp_f32_e32 v222, v238
	v_exp_f32_e32 v238, v239
	s_add_i32 s0, s0, s1
	s_lshl_b32 s1, s69, 8
	v_lshl_or_b32 v130, v175, 3, s1
	s_cmp_gt_u32 s69, 47
	v_or_b32_e32 v240, s0, v176
	v_or_b32_e32 v130, s61, v130
	s_mov_b64 s[0:1], -1
	v_mul_f32_e32 v237, 0xbfb8aa3b, v47
	v_mul_f32_e32 v236, 0xbfb8aa3b, v56
	v_mul_f32_e32 v235, 0xbfb8aa3b, v48
	v_mul_f32_e32 v234, 0xbfb8aa3b, v57
	v_mul_f32_e32 v233, 0xbfb8aa3b, v49
	v_mul_f32_e32 v232, 0xbfb8aa3b, v50
	v_mul_f32_e32 v231, 0xbfb8aa3b, v42
	v_mul_f32_e32 v230, 0xbfb8aa3b, v51
	v_mul_f32_e32 v229, 0xbfb8aa3b, v43
	v_mul_f32_e32 v228, 0xbfb8aa3b, v18
	s_cbranch_scc0 .LBB0_145
	v_add_f32_e32 v178, 1.0, v171
	v_rcp_f32_e32 v179, v178
	v_add_f32_e32 v178, 1.0, v170
	v_add_f32_e32 v134, 1.0, v173
	v_add_f32_e32 v135, 1.0, v133
	v_add_f32_e32 v137, 1.0, v172
	v_rcp_f32_e32 v181, v178
	v_add_f32_e32 v178, 1.0, v169
	v_rcp_f32_e32 v134, v134
	v_rcp_f32_e32 v135, v135
	v_rcp_f32_e32 v137, v137
	v_rcp_f32_e32 v180, v178
	v_add_f32_e32 v178, 1.0, v131
	v_rcp_f32_e32 v182, v178
	v_mov_b32_e32 v0, v240
	v_mov_b32_e32 v136, v130
	v_cvt_pk_bf16_f32 v178, v132, v135
	v_cvt_pk_bf16_f32 v179, v179, v180
	v_cvt_pk_bf16_f32 v180, v134, v137
	v_mov_b64_e32 v[134:135], s[8:9]
	v_ashrrev_i32_e32 v137, 31, v136
	v_cvt_pk_bf16_f32 v181, v181, v182
	v_mad_i64_i32 v[182:183], s[0:1], v0, s47, v[134:135]
	v_lshlrev_b64 v[136:137], 1, v[136:137]
	v_lshl_add_u64 v[182:183], v[182:183], 0, v[136:137]
	global_store_dwordx4 v[182:183], v[178:181], off
	s_nop 1
	v_add_f32_e32 v179, 1.0, v167
	v_add_f32_e32 v178, 1.0, v168
	v_rcp_f32_e32 v180, v179
	v_add_f32_e32 v179, 1.0, v166
	v_add_f32_e32 v181, 1.0, v145
	v_add_f32_e32 v239, 1.0, v144
	v_add_f32_e32 v224, 1.0, v143
	v_add_f32_e32 v225, 1.0, v142
	v_add_f32_e32 v226, 1.0, v141
	v_rcp_f32_e32 v178, v178
	v_rcp_f32_e32 v179, v179
	v_rcp_f32_e32 v181, v181
	v_rcp_f32_e32 v239, v239
	v_rcp_f32_e32 v224, v224
	v_rcp_f32_e32 v225, v225
	v_rcp_f32_e32 v226, v226
	v_cvt_pk_bf16_f32 v178, v178, v179
	v_cvt_pk_bf16_f32 v180, v180, v181
	v_cvt_pk_bf16_f32 v179, v239, v225
	v_cvt_pk_bf16_f32 v181, v224, v226
	global_store_dwordx4 v[182:183], v[178:181], off offset:256
	s_nop 1
	v_add_f32_e32 v179, 1.0, v139
	v_add_f32_e32 v178, 1.0, v140
	v_rcp_f32_e32 v180, v179
	v_add_f32_e32 v179, 1.0, v138
	v_add_f32_e32 v183, 1.0, v155
	v_add_f32_e32 v225, 1.0, v153
	v_rcp_f32_e32 v178, v178
	v_rcp_f32_e32 v179, v179
	v_add_f32_e32 v181, 1.0, v213
	v_rcp_f32_e32 v183, v183
	v_add_f32_e32 v224, 1.0, v154
	v_rcp_f32_e32 v225, v225
	v_add_f32_e32 v226, 1.0, v152
	v_rcp_f32_e32 v181, v181
	v_rcp_f32_e32 v224, v224
	v_rcp_f32_e32 v226, v226
	v_add_u32_e32 v182, 16, v0
	v_cvt_pk_bf16_f32 v178, v178, v179
	v_cvt_pk_bf16_f32 v179, v183, v225
	v_mad_i64_i32 v[182:183], s[0:1], v182, s47, v[134:135]
	v_cvt_pk_bf16_f32 v180, v180, v181
	v_cvt_pk_bf16_f32 v181, v224, v226
	v_lshl_add_u64 v[182:183], v[182:183], 0, v[136:137]
	global_store_dwordx4 v[182:183], v[178:181], off
	s_nop 1
	v_add_f32_e32 v179, 1.0, v211
	v_add_f32_e32 v178, 1.0, v212
	v_rcp_f32_e32 v180, v179
	v_add_f32_e32 v179, 1.0, v252
	v_add_f32_e32 v181, 1.0, v251
	v_add_f32_e32 v224, 1.0, v250
	v_add_f32_e32 v225, 1.0, v249
	v_add_f32_e32 v226, 1.0, v248
	v_add_f32_e32 v239, 1.0, v247
	v_rcp_f32_e32 v178, v178
	v_rcp_f32_e32 v179, v179
	v_rcp_f32_e32 v181, v181
	v_rcp_f32_e32 v224, v224
	v_rcp_f32_e32 v225, v225
	v_rcp_f32_e32 v226, v226
	v_rcp_f32_e32 v239, v239
	v_cvt_pk_bf16_f32 v178, v178, v179
	v_cvt_pk_bf16_f32 v180, v180, v181
	v_cvt_pk_bf16_f32 v179, v224, v226
	v_cvt_pk_bf16_f32 v181, v225, v239
	global_store_dwordx4 v[182:183], v[178:181], off offset:256
	s_nop 1
	v_add_f32_e32 v179, 1.0, v245
	v_add_f32_e32 v178, 1.0, v246
	v_rcp_f32_e32 v180, v179
	v_add_f32_e32 v179, 1.0, v244
	v_add_f32_e32 v183, 1.0, v242
	v_add_f32_e32 v225, 1.0, v184
	v_rcp_f32_e32 v178, v178
	v_rcp_f32_e32 v179, v179
	v_add_f32_e32 v181, 1.0, v243
	v_rcp_f32_e32 v183, v183
	v_add_f32_e32 v224, 1.0, v241
	v_rcp_f32_e32 v225, v225
	v_add_f32_e32 v226, 1.0, v177
	v_rcp_f32_e32 v181, v181
	v_rcp_f32_e32 v224, v224
	v_rcp_f32_e32 v226, v226
	v_add_u32_e32 v182, 32, v0
	v_cvt_pk_bf16_f32 v178, v178, v179
	v_cvt_pk_bf16_f32 v179, v183, v225
	v_mad_i64_i32 v[182:183], s[0:1], v182, s47, v[134:135]
	v_cvt_pk_bf16_f32 v180, v180, v181
	v_cvt_pk_bf16_f32 v181, v224, v226
	v_lshl_add_u64 v[182:183], v[182:183], 0, v[136:137]
	global_store_dwordx4 v[182:183], v[178:181], off
	s_nop 1
	v_add_f32_e32 v179, 1.0, v199
	v_add_f32_e32 v178, 1.0, v198
	v_rcp_f32_e32 v180, v179
	v_add_f32_e32 v179, 1.0, v197
	v_add_f32_e32 v181, 1.0, v196
	v_add_f32_e32 v224, 1.0, v195
	v_add_f32_e32 v225, 1.0, v194
	v_add_f32_e32 v226, 1.0, v193
	v_add_f32_e32 v239, 1.0, v192
	v_rcp_f32_e32 v178, v178
	v_rcp_f32_e32 v179, v179
	v_rcp_f32_e32 v181, v181
	v_rcp_f32_e32 v224, v224
	v_rcp_f32_e32 v225, v225
	v_rcp_f32_e32 v226, v226
	v_rcp_f32_e32 v239, v239
	v_cvt_pk_bf16_f32 v178, v178, v179
	v_cvt_pk_bf16_f32 v180, v180, v181
	v_cvt_pk_bf16_f32 v179, v224, v226
	v_cvt_pk_bf16_f32 v181, v225, v239
	global_store_dwordx4 v[182:183], v[178:181], off offset:256
	s_nop 1
	v_add_f32_e32 v179, 1.0, v190
	v_add_f32_e32 v178, 1.0, v191
	v_rcp_f32_e32 v180, v179
	v_add_f32_e32 v179, 1.0, v189
	v_add_f32_e32 v183, 1.0, v187
	v_add_f32_e32 v225, 1.0, v185
	v_rcp_f32_e32 v178, v178
	v_rcp_f32_e32 v179, v179
	v_add_f32_e32 v181, 1.0, v188
	v_rcp_f32_e32 v183, v183
	v_add_f32_e32 v224, 1.0, v186
	v_rcp_f32_e32 v225, v225
	v_add_f32_e32 v226, 1.0, v201
	v_rcp_f32_e32 v181, v181
	v_rcp_f32_e32 v224, v224
	v_rcp_f32_e32 v226, v226
	v_add_u32_e32 v182, 48, v0
	v_cvt_pk_bf16_f32 v178, v178, v179
	v_cvt_pk_bf16_f32 v179, v183, v225
	v_mad_i64_i32 v[182:183], s[0:1], v182, s47, v[134:135]
	v_cvt_pk_bf16_f32 v180, v180, v181
	v_cvt_pk_bf16_f32 v181, v224, v226
	v_lshl_add_u64 v[182:183], v[182:183], 0, v[136:137]
	global_store_dwordx4 v[182:183], v[178:181], off
	s_nop 1
	v_add_f32_e32 v179, 1.0, v221
	v_add_f32_e32 v178, 1.0, v200
	v_rcp_f32_e32 v180, v179
	v_add_f32_e32 v179, 1.0, v220
	v_add_f32_e32 v181, 1.0, v219
	v_add_f32_e32 v224, 1.0, v218
	v_add_f32_e32 v225, 1.0, v217
	v_add_f32_e32 v226, 1.0, v216
	v_add_f32_e32 v239, 1.0, v215
	v_rcp_f32_e32 v178, v178
	v_rcp_f32_e32 v179, v179
	v_rcp_f32_e32 v181, v181
	v_rcp_f32_e32 v224, v224
	v_rcp_f32_e32 v225, v225
	v_rcp_f32_e32 v226, v226
	v_rcp_f32_e32 v239, v239
	v_cvt_pk_bf16_f32 v178, v178, v179
	v_cvt_pk_bf16_f32 v180, v180, v181
	v_cvt_pk_bf16_f32 v179, v224, v226
	v_cvt_pk_bf16_f32 v181, v225, v239
	global_store_dwordx4 v[182:183], v[178:181], off offset:256
	s_nop 1
	v_add_f32_e32 v179, 1.0, v208
	v_add_f32_e32 v178, 1.0, v209
	v_rcp_f32_e32 v180, v179
	v_add_f32_e32 v179, 1.0, v207
	v_add_f32_e32 v183, 1.0, v205
	v_add_f32_e32 v225, 1.0, v203
	v_rcp_f32_e32 v178, v178
	v_rcp_f32_e32 v179, v179
	v_add_f32_e32 v181, 1.0, v206
	v_rcp_f32_e32 v183, v183
	v_add_f32_e32 v224, 1.0, v204
	v_rcp_f32_e32 v225, v225
	v_add_f32_e32 v226, 1.0, v202
	v_rcp_f32_e32 v181, v181
	v_rcp_f32_e32 v224, v224
	v_rcp_f32_e32 v226, v226
	v_add_u32_e32 v182, 0x80, v0
	v_cvt_pk_bf16_f32 v178, v178, v179
	v_cvt_pk_bf16_f32 v179, v183, v225
	v_mad_i64_i32 v[182:183], s[0:1], v182, s47, v[134:135]
	v_cvt_pk_bf16_f32 v180, v180, v181
	v_cvt_pk_bf16_f32 v181, v224, v226
	v_lshl_add_u64 v[182:183], v[182:183], 0, v[136:137]
	global_store_dwordx4 v[182:183], v[178:181], off
	s_nop 1
	v_add_f32_e32 v179, 1.0, v222
	v_rcp_f32_e32 v180, v179
	v_exp_f32_e32 v179, v237
	v_exp_f32_e32 v224, v236
	v_exp_f32_e32 v226, v234
	v_exp_f32_e32 v239, v233
	v_add_f32_e32 v179, 1.0, v179
	v_rcp_f32_e32 v225, v179
	v_exp_f32_e32 v179, v235
	v_add_f32_e32 v178, 1.0, v223
	v_add_f32_e32 v181, 1.0, v238
	v_add_f32_e32 v224, 1.0, v224
	v_add_f32_e32 v179, 1.0, v179
	v_rcp_f32_e32 v227, v179
	v_add_f32_e32 v179, 1.0, v226
	v_add_f32_e32 v226, 1.0, v239
	v_rcp_f32_e32 v178, v178
	v_rcp_f32_e32 v181, v181
	v_rcp_f32_e32 v224, v224
	v_rcp_f32_e32 v179, v179
	v_rcp_f32_e32 v226, v226
	v_cvt_pk_bf16_f32 v178, v178, v181
	v_cvt_pk_bf16_f32 v180, v180, v225
	v_cvt_pk_bf16_f32 v179, v224, v179
	v_cvt_pk_bf16_f32 v181, v227, v226
	global_store_dwordx4 v[182:183], v[178:181], off offset:256
	s_nop 1
	v_exp_f32_e32 v179, v231
	v_mul_f32_e32 v183, 0xbfb8aa3b, v52
	v_mul_f32_e32 v225, 0xbfb8aa3b, v53
	v_exp_f32_e32 v183, v183
	v_add_f32_e32 v179, 1.0, v179
	v_rcp_f32_e32 v181, v179
	v_exp_f32_e32 v179, v229
	v_exp_f32_e32 v225, v225
	v_mul_f32_e32 v226, 0xbfb8aa3b, v45
	v_exp_f32_e32 v178, v232
	v_add_f32_e32 v179, 1.0, v179
	v_rcp_f32_e32 v224, v179
	v_mul_f32_e32 v179, 0xbfb8aa3b, v44
	v_exp_f32_e32 v179, v179
	v_exp_f32_e32 v180, v230
	v_exp_f32_e32 v226, v226
	v_add_f32_e32 v183, 1.0, v183
	v_add_f32_e32 v179, 1.0, v179
	v_rcp_f32_e32 v227, v179
	v_add_f32_e32 v179, 1.0, v225
	v_add_f32_e32 v178, 1.0, v178
	v_add_f32_e32 v180, 1.0, v180
	v_rcp_f32_e32 v183, v183
	v_rcp_f32_e32 v179, v179
	v_add_f32_e32 v225, 1.0, v226
	v_rcp_f32_e32 v178, v178
	v_rcp_f32_e32 v180, v180
	v_rcp_f32_e32 v225, v225
	v_add_u32_e32 v182, 0x90, v0
	v_cvt_pk_bf16_f32 v179, v183, v179
	v_mad_i64_i32 v[182:183], s[0:1], v182, s47, v[134:135]
	v_cvt_pk_bf16_f32 v178, v178, v180
	v_cvt_pk_bf16_f32 v180, v181, v224
	v_cvt_pk_bf16_f32 v181, v227, v225
	v_lshl_add_u64 v[182:183], v[182:183], 0, v[136:137]
	global_store_dwordx4 v[182:183], v[178:181], off
	s_nop 1
	v_mul_f32_e32 v179, 0xbfb8aa3b, v30
	v_exp_f32_e32 v179, v179
	v_mul_f32_e32 v178, 0xbfb8aa3b, v38
	v_mul_f32_e32 v180, 0xbfb8aa3b, v39
	v_mul_f32_e32 v224, 0xbfb8aa3b, v40
	v_add_f32_e32 v179, 1.0, v179
	v_rcp_f32_e32 v181, v179
	v_mul_f32_e32 v179, 0xbfb8aa3b, v31
	v_exp_f32_e32 v179, v179
	v_mul_f32_e32 v226, 0xbfb8aa3b, v41
	v_mul_f32_e32 v227, 0xbfb8aa3b, v33
	v_exp_f32_e32 v178, v178
	v_add_f32_e32 v179, 1.0, v179
	v_rcp_f32_e32 v225, v179
	v_mul_f32_e32 v179, 0xbfb8aa3b, v32
	v_exp_f32_e32 v179, v179
	v_exp_f32_e32 v180, v180
	v_exp_f32_e32 v224, v224
	v_exp_f32_e32 v226, v226
	v_exp_f32_e32 v227, v227
	v_add_f32_e32 v179, 1.0, v179
	v_add_f32_e32 v178, 1.0, v178
	v_add_f32_e32 v180, 1.0, v180
	v_add_f32_e32 v224, 1.0, v224
	v_rcp_f32_e32 v239, v179
	v_add_f32_e32 v179, 1.0, v226
	v_add_f32_e32 v226, 1.0, v227
	v_rcp_f32_e32 v178, v178
	v_rcp_f32_e32 v180, v180
	v_rcp_f32_e32 v224, v224
	v_rcp_f32_e32 v179, v179
	v_rcp_f32_e32 v226, v226
	v_cvt_pk_bf16_f32 v178, v178, v180
	v_cvt_pk_bf16_f32 v180, v181, v225
	v_cvt_pk_bf16_f32 v179, v224, v179
	v_cvt_pk_bf16_f32 v181, v239, v226
	global_store_dwordx4 v[182:183], v[178:181], off offset:256
	s_nop 1
	v_mul_f32_e32 v179, 0xbfb8aa3b, v26
	v_exp_f32_e32 v179, v179
	v_mul_f32_e32 v183, 0xbfb8aa3b, v36
	v_mul_f32_e32 v225, 0xbfb8aa3b, v37
	v_mul_f32_e32 v178, 0xbfb8aa3b, v34
	v_add_f32_e32 v179, 1.0, v179
	v_rcp_f32_e32 v181, v179
	v_mul_f32_e32 v179, 0xbfb8aa3b, v27
	v_exp_f32_e32 v179, v179
	v_mul_f32_e32 v180, 0xbfb8aa3b, v35
	v_exp_f32_e32 v183, v183
	v_exp_f32_e32 v225, v225
	v_add_f32_e32 v179, 1.0, v179
	v_rcp_f32_e32 v224, v179
	v_mul_f32_e32 v179, 0xbfb8aa3b, v28
	v_exp_f32_e32 v179, v179
	v_mul_f32_e32 v226, 0xbfb8aa3b, v29
	v_exp_f32_e32 v178, v178
	v_exp_f32_e32 v180, v180
	v_exp_f32_e32 v226, v226
	v_add_f32_e32 v179, 1.0, v179
	v_add_f32_e32 v183, 1.0, v183
	v_rcp_f32_e32 v227, v179
	v_add_f32_e32 v179, 1.0, v225
	v_add_f32_e32 v178, 1.0, v178
	v_add_f32_e32 v180, 1.0, v180
	v_rcp_f32_e32 v183, v183
	v_rcp_f32_e32 v179, v179
	v_add_f32_e32 v225, 1.0, v226
	v_rcp_f32_e32 v178, v178
	v_rcp_f32_e32 v180, v180
	v_rcp_f32_e32 v225, v225
	v_add_u32_e32 v182, 0xa0, v0
	v_cvt_pk_bf16_f32 v179, v183, v179
	v_mad_i64_i32 v[182:183], s[0:1], v182, s47, v[134:135]
	v_cvt_pk_bf16_f32 v178, v178, v180
	v_cvt_pk_bf16_f32 v180, v181, v224
	v_cvt_pk_bf16_f32 v181, v227, v225
	v_lshl_add_u64 v[182:183], v[182:183], 0, v[136:137]
	global_store_dwordx4 v[182:183], v[178:181], off
	s_nop 1
	v_mul_f32_e32 v179, 0xbfb8aa3b, v14
	v_exp_f32_e32 v179, v179
	v_mul_f32_e32 v178, 0xbfb8aa3b, v22
	v_mul_f32_e32 v180, 0xbfb8aa3b, v23
	v_mul_f32_e32 v224, 0xbfb8aa3b, v24
	v_add_f32_e32 v179, 1.0, v179
	v_rcp_f32_e32 v181, v179
	v_mul_f32_e32 v179, 0xbfb8aa3b, v15
	v_exp_f32_e32 v179, v179
	v_mul_f32_e32 v226, 0xbfb8aa3b, v25
	v_mul_f32_e32 v227, 0xbfb8aa3b, v17
	v_exp_f32_e32 v178, v178
	v_add_f32_e32 v179, 1.0, v179
	v_rcp_f32_e32 v225, v179
	v_mul_f32_e32 v179, 0xbfb8aa3b, v16
	v_exp_f32_e32 v179, v179
	v_exp_f32_e32 v180, v180
	v_exp_f32_e32 v224, v224
	v_exp_f32_e32 v226, v226
	v_exp_f32_e32 v227, v227
	v_add_f32_e32 v179, 1.0, v179
	v_add_f32_e32 v178, 1.0, v178
	v_add_f32_e32 v180, 1.0, v180
	v_add_f32_e32 v224, 1.0, v224
	v_rcp_f32_e32 v239, v179
	v_add_f32_e32 v179, 1.0, v226
	v_add_f32_e32 v226, 1.0, v227
	v_rcp_f32_e32 v178, v178
	v_rcp_f32_e32 v180, v180
	v_rcp_f32_e32 v224, v224
	v_rcp_f32_e32 v179, v179
	v_rcp_f32_e32 v226, v226
	v_cvt_pk_bf16_f32 v178, v178, v180
	v_cvt_pk_bf16_f32 v180, v181, v225
	v_cvt_pk_bf16_f32 v179, v224, v179
	v_cvt_pk_bf16_f32 v181, v239, v226
	global_store_dwordx4 v[182:183], v[178:181], off offset:256
	s_nop 1
	v_mul_f32_e32 v179, 0xbfb8aa3b, v10
	v_exp_f32_e32 v179, v179
	v_mul_f32_e32 v180, 0xbfb8aa3b, v19
	v_mul_f32_e32 v181, 0xbfb8aa3b, v11
	v_exp_f32_e32 v180, v180
	v_exp_f32_e32 v181, v181
	v_add_f32_e32 v179, 1.0, v179
	v_rcp_f32_e32 v182, v179
	v_add_f32_e32 v179, 1.0, v180
	v_add_f32_e32 v180, 1.0, v181
	v_mul_f32_e32 v181, 0xbfb8aa3b, v20
	v_mul_f32_e32 v183, 0xbfb8aa3b, v12
	v_mul_f32_e32 v224, 0xbfb8aa3b, v21
	v_mul_f32_e32 v225, 0xbfb8aa3b, v13
	v_exp_f32_e32 v178, v228
	v_exp_f32_e32 v181, v181
	v_exp_f32_e32 v183, v183
	v_exp_f32_e32 v224, v224
	v_exp_f32_e32 v225, v225
	v_add_f32_e32 v178, 1.0, v178
	v_add_f32_e32 v181, 1.0, v181
	v_add_f32_e32 v183, 1.0, v183
	v_add_f32_e32 v224, 1.0, v224
	v_add_f32_e32 v225, 1.0, v225
	v_rcp_f32_e32 v178, v178
	v_rcp_f32_e32 v179, v179
	v_rcp_f32_e32 v180, v180
	v_rcp_f32_e32 v181, v181
	v_rcp_f32_e32 v183, v183
	v_rcp_f32_e32 v224, v224
	v_rcp_f32_e32 v225, v225
	v_add_u32_e32 v0, 0xb0, v0
	v_mad_i64_i32 v[134:135], s[0:1], v0, s47, v[134:135]
	v_cvt_pk_bf16_f32 v178, v178, v179
	v_cvt_pk_bf16_f32 v179, v181, v224
	v_cvt_pk_bf16_f32 v180, v182, v180
	v_cvt_pk_bf16_f32 v181, v183, v225
	v_lshl_add_u64 v[182:183], v[134:135], 0, v[136:137]
	global_store_dwordx4 v[182:183], v[178:181], off
	v_mul_f32_e32 v134, 0xbfb8aa3b, v2
	v_exp_f32_e32 v134, v134
	v_mul_f32_e32 v135, 0xbfb8aa3b, v7
	v_mul_f32_e32 v136, 0xbfb8aa3b, v3
	v_exp_f32_e32 v135, v135
	v_exp_f32_e32 v136, v136
	v_add_f32_e32 v134, 1.0, v134
	v_rcp_f32_e32 v137, v134
	v_add_f32_e32 v134, 1.0, v135
	v_add_f32_e32 v135, 1.0, v136
	v_mul_f32_e32 v136, 0xbfb8aa3b, v8
	v_mul_f32_e32 v178, 0xbfb8aa3b, v4
	v_exp_f32_e32 v136, v136
	v_exp_f32_e32 v178, v178
	v_mul_f32_e32 v0, 0xbfb8aa3b, v6
	v_rcp_f32_e32 v179, v135
	v_add_f32_e32 v135, 1.0, v136
	v_add_f32_e32 v136, 1.0, v178
	v_mul_f32_e32 v178, 0xbfb8aa3b, v9
	v_mul_f32_e32 v180, 0xbfb8aa3b, v5
	v_exp_f32_e32 v0, v0
	v_exp_f32_e32 v178, v178
	v_exp_f32_e32 v180, v180
	v_rcp_f32_e32 v181, v136
	v_add_f32_e32 v0, 1.0, v0
	v_add_f32_e32 v136, 1.0, v178
	v_add_f32_e32 v178, 1.0, v180
	v_rcp_f32_e32 v0, v0
	v_rcp_f32_e32 v134, v134
	v_rcp_f32_e32 v135, v135
	v_rcp_f32_e32 v136, v136
	v_rcp_f32_e32 v178, v178
	v_cvt_pk_bf16_f32 v134, v0, v134
	v_cvt_pk_bf16_f32 v135, v135, v136
	v_cvt_pk_bf16_f32 v136, v137, v179
	v_cvt_pk_bf16_f32 v137, v181, v178
	global_store_dwordx4 v[182:183], v[134:137], off offset:256
	s_mov_b64 s[0:1], 0

.LBB0_727:
	s_add_i32 s14, s14, 2
	s_add_u32 s40, s30, s12
	s_addc_u32 s41, s31, s13
	s_add_u32 s84, s26, s12
	s_addc_u32 s85, s27, s13
	s_add_i32 s86, 0, 0x10000
	ds_read_b128 v[134:137], v224
	ds_read_b128 v[152:155], v224 offset:1024
	ds_read_b128 v[162:165], v224 offset:2048
	ds_read_b128 v[166:169], v224 offset:3072
	s_cmp_eq_u32 s12, s22
	s_cselect_b32 s61, s51, s41
	s_cselect_b32 s60, s50, s40
	s_cselect_b32 s41, s49, s85
	s_cselect_b32 s40, s80, s84
	v_lshl_add_u64 v[202:203], v[132:133], 0, s[12:13]
	s_add_i32 m0, s66, 0xc000
	ds_read_b128 v[170:173], v160
	ds_read_b128 v[174:177], v160 offset:1024
	ds_read_b128 v[178:181], v160 offset:2048
	ds_read_b128 v[182:185], v160 offset:3072
	ds_read_b128 v[186:189], v160 offset:4096
	ds_read_b128 v[190:193], v160 offset:5120
	ds_read_b128 v[194:197], v160 offset:6144
	ds_read_b128 v[198:201], v160 offset:7168
	global_load_lds_dwordx4 v[202:203], off
	v_lshl_add_u64 v[202:203], v[130:131], 0, s[12:13]
	s_add_i32 m0, s66, 0xe000
	s_nop 0
	global_load_lds_dwordx4 v[202:203], off
	s_waitcnt lgkmcnt(8)
	s_barrier
	s_waitcnt lgkmcnt(7)
	v_mfma_f32_16x16x32_bf16 v[126:129], v[134:137], v[170:173], v[126:129]
	v_mfma_f32_16x16x32_bf16 v[122:125], v[162:165], v[170:173], v[122:125]
	s_waitcnt lgkmcnt(5)
	v_mfma_f32_16x16x32_bf16 v[110:113], v[134:137], v[178:181], v[110:113]
	v_mfma_f32_16x16x32_bf16 v[106:109], v[162:165], v[178:181], v[106:109]
	s_waitcnt lgkmcnt(3)
	v_mfma_f32_16x16x32_bf16 v[94:97], v[134:137], v[186:189], v[94:97]
	v_mfma_f32_16x16x32_bf16 v[90:93], v[162:165], v[186:189], v[90:93]
	s_waitcnt lgkmcnt(1)
	v_mfma_f32_16x16x32_bf16 v[78:81], v[134:137], v[194:197], v[78:81]
	v_mfma_f32_16x16x32_bf16 v[74:77], v[162:165], v[194:197], v[74:77]
	v_mfma_f32_16x16x32_bf16 v[126:129], v[152:155], v[174:177], v[126:129]
	v_mfma_f32_16x16x32_bf16 v[122:125], v[166:169], v[174:177], v[122:125]
	v_mfma_f32_16x16x32_bf16 v[110:113], v[152:155], v[182:185], v[110:113]
	v_mfma_f32_16x16x32_bf16 v[106:109], v[166:169], v[182:185], v[106:109]
	v_mfma_f32_16x16x32_bf16 v[94:97], v[152:155], v[190:193], v[94:97]
	v_mfma_f32_16x16x32_bf16 v[90:93], v[166:169], v[190:193], v[90:93]
	s_waitcnt lgkmcnt(0)
	v_mfma_f32_16x16x32_bf16 v[78:81], v[152:155], v[198:201], v[78:81]
	v_mfma_f32_16x16x32_bf16 v[74:77], v[166:169], v[198:201], v[74:77]
	s_barrier
	s_add_i32 s87, 0, 0x14000
	s_add_i32 s84, s86, s65
	s_mov_b32 m0, s84
	ds_read_b128 v[202:205], v225
	ds_read_b128 v[206:209], v225 offset:1024
	ds_read_b128 v[216:219], v225 offset:2048
	global_load_lds_dwordx4 v0, s[40:41]
	s_add_i32 m0, s84, 0x2000
	ds_read_b128 v[220:223], v225 offset:3072
	global_load_lds_dwordx4 v138, s[40:41]
	s_barrier
	s_waitcnt lgkmcnt(3)
	v_mfma_f32_16x16x32_bf16 v[118:121], v[202:205], v[170:173], v[118:121]
	s_waitcnt lgkmcnt(1)
	v_mfma_f32_16x16x32_bf16 v[114:117], v[216:219], v[170:173], v[114:117]
	v_mfma_f32_16x16x32_bf16 v[102:105], v[202:205], v[178:181], v[102:105]
	v_mfma_f32_16x16x32_bf16 v[98:101], v[216:219], v[178:181], v[98:101]
	v_mfma_f32_16x16x32_bf16 v[86:89], v[202:205], v[186:189], v[86:89]
	v_mfma_f32_16x16x32_bf16 v[82:85], v[216:219], v[186:189], v[82:85]
	v_mfma_f32_16x16x32_bf16 v[70:73], v[202:205], v[194:197], v[70:73]
	v_mfma_f32_16x16x32_bf16 v[66:69], v[216:219], v[194:197], v[66:69]
	v_mfma_f32_16x16x32_bf16 v[118:121], v[206:209], v[174:177], v[118:121]
	s_waitcnt lgkmcnt(0)
	v_mfma_f32_16x16x32_bf16 v[114:117], v[220:223], v[174:177], v[114:117]
	v_mfma_f32_16x16x32_bf16 v[102:105], v[206:209], v[182:185], v[102:105]
	v_mfma_f32_16x16x32_bf16 v[98:101], v[220:223], v[182:185], v[98:101]
	v_mfma_f32_16x16x32_bf16 v[86:89], v[206:209], v[190:193], v[86:89]
	v_mfma_f32_16x16x32_bf16 v[82:85], v[220:223], v[190:193], v[82:85]
	v_mfma_f32_16x16x32_bf16 v[70:73], v[206:209], v[198:201], v[70:73]
	v_mfma_f32_16x16x32_bf16 v[66:69], v[220:223], v[198:201], v[66:69]
	s_mov_b32 m0, s66
	s_add_u32 s98, s60, 0x80
	s_addc_u32 s99, s61, 0
	s_barrier
	ds_read_b128 v[170:173], v160 offset:16384
	ds_read_b128 v[174:177], v160 offset:17408
	ds_read_b128 v[178:181], v160 offset:18432
	ds_read_b128 v[182:185], v160 offset:19456
	ds_read_b128 v[186:189], v160 offset:20480
	ds_read_b128 v[190:193], v160 offset:21504
	ds_read_b128 v[194:197], v160 offset:22528
	global_load_lds_dwordx4 v142, s[60:61]
	s_mov_b32 m0, s67
	ds_read_b128 v[198:201], v160 offset:23552
	global_load_lds_dwordx4 v140, s[60:61]
	s_barrier
	s_waitcnt lgkmcnt(7)
	v_mfma_f32_16x16x32_bf16 v[62:65], v[134:137], v[170:173], v[62:65]
	v_mfma_f32_16x16x32_bf16 v[58:61], v[162:165], v[170:173], v[58:61]
	s_waitcnt lgkmcnt(5)
	v_mfma_f32_16x16x32_bf16 v[46:49], v[134:137], v[178:181], v[46:49]
	v_mfma_f32_16x16x32_bf16 v[42:45], v[162:165], v[178:181], v[42:45]
	s_waitcnt lgkmcnt(3)
	v_mfma_f32_16x16x32_bf16 v[30:33], v[134:137], v[186:189], v[30:33]
	v_mfma_f32_16x16x32_bf16 v[26:29], v[162:165], v[186:189], v[26:29]
	s_waitcnt lgkmcnt(1)
	v_mfma_f32_16x16x32_bf16 v[14:17], v[134:137], v[194:197], v[14:17]
	v_mfma_f32_16x16x32_bf16 v[10:13], v[162:165], v[194:197], v[10:13]
	v_mfma_f32_16x16x32_bf16 v[62:65], v[152:155], v[174:177], v[62:65]
	v_mfma_f32_16x16x32_bf16 v[58:61], v[166:169], v[174:177], v[58:61]
	v_mfma_f32_16x16x32_bf16 v[46:49], v[152:155], v[182:185], v[46:49]
	v_mfma_f32_16x16x32_bf16 v[42:45], v[166:169], v[182:185], v[42:45]
	v_mfma_f32_16x16x32_bf16 v[30:33], v[152:155], v[190:193], v[30:33]
	v_mfma_f32_16x16x32_bf16 v[26:29], v[166:169], v[190:193], v[26:29]
	s_waitcnt lgkmcnt(0)
	v_mfma_f32_16x16x32_bf16 v[14:17], v[152:155], v[198:201], v[14:17]
	v_mfma_f32_16x16x32_bf16 v[10:13], v[166:169], v[198:201], v[10:13]
	s_barrier
	s_add_i32 s86, s87, s65
	s_mov_b32 m0, s86
	s_add_u32 s84, s40, 0x100000
	s_addc_u32 s85, s41, 0
	global_load_lds_dwordx4 v0, s[84:85]
	s_add_i32 m0, s86, 0x2000
	s_nop 0
	global_load_lds_dwordx4 v138, s[84:85]
	s_waitcnt vmcnt(6)
	s_barrier
	v_mfma_f32_16x16x32_bf16 v[54:57], v[202:205], v[170:173], v[54:57]
	v_mfma_f32_16x16x32_bf16 v[50:53], v[216:219], v[170:173], v[50:53]
	v_mfma_f32_16x16x32_bf16 v[38:41], v[202:205], v[178:181], v[38:41]
	v_mfma_f32_16x16x32_bf16 v[34:37], v[216:219], v[178:181], v[34:37]
	v_mfma_f32_16x16x32_bf16 v[22:25], v[202:205], v[186:189], v[22:25]
	v_mfma_f32_16x16x32_bf16 v[18:21], v[216:219], v[186:189], v[18:21]
	v_mfma_f32_16x16x32_bf16 v[6:9], v[202:205], v[194:197], v[6:9]
	v_mfma_f32_16x16x32_bf16 v[2:5], v[216:219], v[194:197], v[2:5]
	v_mfma_f32_16x16x32_bf16 v[54:57], v[206:209], v[174:177], v[54:57]
	v_mfma_f32_16x16x32_bf16 v[50:53], v[220:223], v[174:177], v[50:53]
	v_mfma_f32_16x16x32_bf16 v[38:41], v[206:209], v[182:185], v[38:41]
	v_mfma_f32_16x16x32_bf16 v[34:37], v[220:223], v[182:185], v[34:37]
	v_mfma_f32_16x16x32_bf16 v[22:25], v[206:209], v[190:193], v[22:25]
	v_mfma_f32_16x16x32_bf16 v[18:21], v[220:223], v[190:193], v[18:21]
	v_mfma_f32_16x16x32_bf16 v[6:9], v[206:209], v[198:201], v[6:9]
	v_mfma_f32_16x16x32_bf16 v[2:5], v[220:223], v[198:201], v[2:5]
	s_add_i32 s84, 0, 0x18000
	s_barrier
	ds_read_b128 v[134:137], v226
	ds_read_b128 v[152:155], v226 offset:1024
	ds_read_b128 v[162:165], v226 offset:2048
	ds_read_b128 v[166:169], v226 offset:3072
	s_add_u32 s60, s60, 0x100000
	s_addc_u32 s61, s61, 0
	s_mov_b32 m0, s68
	ds_read_b128 v[170:173], v160 offset:32768
	ds_read_b128 v[174:177], v160 offset:33792
	ds_read_b128 v[178:181], v160 offset:34816
	ds_read_b128 v[182:185], v160 offset:35840
	ds_read_b128 v[186:189], v160 offset:36864
	ds_read_b128 v[190:193], v160 offset:37888
	ds_read_b128 v[194:197], v160 offset:38912
	global_load_lds_dwordx4 v142, s[60:61]
	s_mov_b32 m0, s69
	ds_read_b128 v[198:201], v160 offset:39936
	global_load_lds_dwordx4 v140, s[60:61]
	s_waitcnt lgkmcnt(8)
	s_barrier
	s_waitcnt lgkmcnt(7)
	v_mfma_f32_16x16x32_bf16 v[126:129], v[134:137], v[170:173], v[126:129]
	v_mfma_f32_16x16x32_bf16 v[122:125], v[162:165], v[170:173], v[122:125]
	s_waitcnt lgkmcnt(5)
	v_mfma_f32_16x16x32_bf16 v[110:113], v[134:137], v[178:181], v[110:113]
	v_mfma_f32_16x16x32_bf16 v[106:109], v[162:165], v[178:181], v[106:109]
	s_waitcnt lgkmcnt(3)
	v_mfma_f32_16x16x32_bf16 v[94:97], v[134:137], v[186:189], v[94:97]
	v_mfma_f32_16x16x32_bf16 v[90:93], v[162:165], v[186:189], v[90:93]
	s_waitcnt lgkmcnt(1)
	v_mfma_f32_16x16x32_bf16 v[78:81], v[134:137], v[194:197], v[78:81]
	v_mfma_f32_16x16x32_bf16 v[74:77], v[162:165], v[194:197], v[74:77]
	v_mfma_f32_16x16x32_bf16 v[126:129], v[152:155], v[174:177], v[126:129]
	v_mfma_f32_16x16x32_bf16 v[122:125], v[166:169], v[174:177], v[122:125]
	v_mfma_f32_16x16x32_bf16 v[110:113], v[152:155], v[182:185], v[110:113]
	v_mfma_f32_16x16x32_bf16 v[106:109], v[166:169], v[182:185], v[106:109]
	v_mfma_f32_16x16x32_bf16 v[94:97], v[152:155], v[190:193], v[94:97]
	v_mfma_f32_16x16x32_bf16 v[90:93], v[166:169], v[190:193], v[90:93]
	s_waitcnt lgkmcnt(0)
	v_mfma_f32_16x16x32_bf16 v[78:81], v[152:155], v[198:201], v[78:81]
	v_mfma_f32_16x16x32_bf16 v[74:77], v[166:169], v[198:201], v[74:77]
	s_barrier
	s_add_i32 s60, 0, 0x1c000
	s_add_i32 s61, s84, s65
	s_add_u32 s100, s40, 0x80
	s_addc_u32 s101, s41, 0
	s_mov_b32 m0, s61
	ds_read_b128 v[202:205], v227
	ds_read_b128 v[206:209], v227 offset:1024
	ds_read_b128 v[216:219], v227 offset:2048
	global_load_lds_dwordx4 v0, s[100:101]
	s_add_i32 m0, s61, 0x2000
	ds_read_b128 v[220:223], v227 offset:3072
	global_load_lds_dwordx4 v138, s[100:101]
	s_barrier
	s_waitcnt lgkmcnt(3)
	v_mfma_f32_16x16x32_bf16 v[118:121], v[202:205], v[170:173], v[118:121]
	s_waitcnt lgkmcnt(1)
	v_mfma_f32_16x16x32_bf16 v[114:117], v[216:219], v[170:173], v[114:117]
	v_mfma_f32_16x16x32_bf16 v[102:105], v[202:205], v[178:181], v[102:105]
	v_mfma_f32_16x16x32_bf16 v[98:101], v[216:219], v[178:181], v[98:101]
	v_mfma_f32_16x16x32_bf16 v[86:89], v[202:205], v[186:189], v[86:89]
	v_mfma_f32_16x16x32_bf16 v[82:85], v[216:219], v[186:189], v[82:85]
	v_mfma_f32_16x16x32_bf16 v[70:73], v[202:205], v[194:197], v[70:73]
	v_mfma_f32_16x16x32_bf16 v[66:69], v[216:219], v[194:197], v[66:69]
	v_mfma_f32_16x16x32_bf16 v[118:121], v[206:209], v[174:177], v[118:121]
	s_waitcnt lgkmcnt(0)
	v_mfma_f32_16x16x32_bf16 v[114:117], v[220:223], v[174:177], v[114:117]
	v_mfma_f32_16x16x32_bf16 v[102:105], v[206:209], v[182:185], v[102:105]
	v_mfma_f32_16x16x32_bf16 v[98:101], v[220:223], v[182:185], v[98:101]
	v_mfma_f32_16x16x32_bf16 v[86:89], v[206:209], v[190:193], v[86:89]
	v_mfma_f32_16x16x32_bf16 v[82:85], v[220:223], v[190:193], v[82:85]
	v_mfma_f32_16x16x32_bf16 v[70:73], v[206:209], v[198:201], v[70:73]
	v_mfma_f32_16x16x32_bf16 v[66:69], v[220:223], v[198:201], v[66:69]
	s_mov_b32 m0, s76
	s_barrier
	ds_read_b128 v[170:173], v160 offset:49152
	ds_read_b128 v[174:177], v160 offset:50176
	ds_read_b128 v[178:181], v160 offset:51200
	ds_read_b128 v[182:185], v160 offset:52224
	ds_read_b128 v[186:189], v160 offset:53248
	ds_read_b128 v[190:193], v160 offset:54272
	ds_read_b128 v[194:197], v160 offset:55296
	global_load_lds_dwordx4 v142, s[98:99]
	s_mov_b32 m0, s77
	ds_read_b128 v[198:201], v160 offset:56320
	global_load_lds_dwordx4 v140, s[98:99]
	s_barrier
	s_waitcnt lgkmcnt(7)
	v_mfma_f32_16x16x32_bf16 v[62:65], v[134:137], v[170:173], v[62:65]
	v_mfma_f32_16x16x32_bf16 v[58:61], v[162:165], v[170:173], v[58:61]
	s_waitcnt lgkmcnt(5)
	v_mfma_f32_16x16x32_bf16 v[46:49], v[134:137], v[178:181], v[46:49]
	v_mfma_f32_16x16x32_bf16 v[42:45], v[162:165], v[178:181], v[42:45]
	s_waitcnt lgkmcnt(3)
	v_mfma_f32_16x16x32_bf16 v[30:33], v[134:137], v[186:189], v[30:33]
	v_mfma_f32_16x16x32_bf16 v[26:29], v[162:165], v[186:189], v[26:29]
	s_waitcnt lgkmcnt(1)
	v_mfma_f32_16x16x32_bf16 v[14:17], v[134:137], v[194:197], v[14:17]
	v_mfma_f32_16x16x32_bf16 v[10:13], v[162:165], v[194:197], v[10:13]
	v_mfma_f32_16x16x32_bf16 v[62:65], v[152:155], v[174:177], v[62:65]
	v_mfma_f32_16x16x32_bf16 v[58:61], v[166:169], v[174:177], v[58:61]
	v_mfma_f32_16x16x32_bf16 v[46:49], v[152:155], v[182:185], v[46:49]
	v_mfma_f32_16x16x32_bf16 v[42:45], v[166:169], v[182:185], v[42:45]
	v_mfma_f32_16x16x32_bf16 v[30:33], v[152:155], v[190:193], v[30:33]
	v_mfma_f32_16x16x32_bf16 v[26:29], v[166:169], v[190:193], v[26:29]
	s_waitcnt lgkmcnt(0)
	v_mfma_f32_16x16x32_bf16 v[14:17], v[152:155], v[198:201], v[14:17]
	v_mfma_f32_16x16x32_bf16 v[10:13], v[166:169], v[198:201], v[10:13]
	s_barrier
	s_add_i32 s60, s60, s65
	s_mov_b32 m0, s60
	s_add_u32 s40, s40, 0x100080
	s_addc_u32 s41, s41, 0
	global_load_lds_dwordx4 v0, s[40:41]
	s_add_i32 m0, s60, 0x2000
	s_nop 0
	global_load_lds_dwordx4 v138, s[40:41]
	s_waitcnt vmcnt(6)
	s_barrier
	v_mfma_f32_16x16x32_bf16 v[54:57], v[202:205], v[170:173], v[54:57]
	v_mfma_f32_16x16x32_bf16 v[50:53], v[216:219], v[170:173], v[50:53]
	v_mfma_f32_16x16x32_bf16 v[38:41], v[202:205], v[178:181], v[38:41]
	v_mfma_f32_16x16x32_bf16 v[34:37], v[216:219], v[178:181], v[34:37]
	v_mfma_f32_16x16x32_bf16 v[22:25], v[202:205], v[186:189], v[22:25]
	v_mfma_f32_16x16x32_bf16 v[18:21], v[216:219], v[186:189], v[18:21]
	v_mfma_f32_16x16x32_bf16 v[6:9], v[202:205], v[194:197], v[6:9]
	v_mfma_f32_16x16x32_bf16 v[2:5], v[216:219], v[194:197], v[2:5]
	v_mfma_f32_16x16x32_bf16 v[54:57], v[206:209], v[174:177], v[54:57]
	v_mfma_f32_16x16x32_bf16 v[50:53], v[220:223], v[174:177], v[50:53]
	v_mfma_f32_16x16x32_bf16 v[38:41], v[206:209], v[182:185], v[38:41]
	v_mfma_f32_16x16x32_bf16 v[34:37], v[220:223], v[182:185], v[34:37]
	v_mfma_f32_16x16x32_bf16 v[22:25], v[206:209], v[190:193], v[22:25]
	v_mfma_f32_16x16x32_bf16 v[18:21], v[220:223], v[190:193], v[18:21]
	v_mfma_f32_16x16x32_bf16 v[6:9], v[206:209], v[198:201], v[6:9]
	v_mfma_f32_16x16x32_bf16 v[2:5], v[220:223], v[198:201], v[2:5]
	s_add_u32 s30, s30, 0x100
	s_addc_u32 s31, s31, 0
	s_add_u32 s26, s26, 0x100
	s_addc_u32 s27, s27, 0
	s_add_u32 s22, s22, 0xffffff00
	s_addc_u32 s23, s23, -1
	v_lshl_add_u64 v[132:133], v[132:133], 0, s[18:19]
	s_cmp_ge_u32 s14, vcc_lo
	v_lshl_add_u64 v[130:131], v[130:131], 0, s[18:19]
	s_barrier
	s_cbranch_scc0 .LBB0_727
	s_mov_b32 s14, 32
	s_mov_b64 s[26:27], 0
	s_andn2_b64 vcc, exec, s[6:7]
	s_mov_b64 s[6:7], -1
	s_cbranch_vccnz .LBB0_724
	v_mov_b32_e32 v130, v148
	v_mov_b64_e32 v[134:135], s[38:39]
	v_and_or_b32 v132, v130, 15, s82
	v_lshrrev_b32_e32 v130, 1, v130
	v_and_or_b32 v130, v130, 24, s75
	v_or_b32_e32 v130, s81, v130
	s_mov_b32 s14, s48
	v_ashrrev_i32_e32 v131, 31, v130
	v_mad_i64_i32 v[136:137], s[0:1], v132, s47, v[134:135]
	v_lshlrev_b64 v[130:131], 1, v[130:131]
	v_lshl_add_u64 v[136:137], v[136:137], 0, v[130:131]
	v_add_co_u32_e32 v152, vcc, s72, v136
	v_ashrrev_i32_e32 v133, 31, v132
	s_nop 0
	v_addc_co_u32_e32 v153, vcc, 0, v137, vcc
	global_load_dwordx4 v[152:155], v[152:153], off
	v_lshlrev_b64 v[156:157], 12, v[132:133]
	v_lshl_add_u64 v[156:157], s[28:29], 0, v[156:157]
	v_lshl_add_u64 v[156:157], v[156:157], 0, v[130:131]
	v_lshl_add_u64 v[136:137], v[136:137], 0, s[34:35]
	s_mov_b32 s22, s79
	s_mov_b64 s[6:7], s[52:53]
	s_mov_b64 s[12:13], s[50:51]
	s_waitcnt vmcnt(0)
	v_lshlrev_b32_e32 v158, 16, v152
	v_and_b32_e32 v159, 0xffff0000, v152
	v_lshlrev_b32_e32 v152, 16, v153
	v_and_b32_e32 v153, 0xffff0000, v153
	v_lshlrev_b32_e32 v162, 16, v154
	v_and_b32_e32 v163, 0xffff0000, v154
	v_lshlrev_b32_e32 v154, 16, v155
	v_and_b32_e32 v155, 0xffff0000, v155
	v_pk_mul_f32 v[128:129], v[128:129], v[152:153]
	v_pk_mul_f32 v[126:127], v[126:127], v[158:159]
	v_pk_mul_f32 v[152:153], v[124:125], v[154:155]
	v_pk_mul_f32 v[124:125], v[122:123], v[162:163]
	v_cvt_pk_bf16_f32 v122, v126, v127
	v_cvt_pk_bf16_f32 v123, v128, v129
	v_cvt_pk_bf16_f32 v124, v124, v125
	v_cvt_pk_bf16_f32 v125, v152, v153
	global_store_dwordx4 v[156:157], v[122:125], off
	global_load_dwordx4 v[122:125], v[136:137], off offset:256
	v_add_u32_e32 v126, 16, v132
	v_mad_i64_i32 v[128:129], s[0:1], v126, s47, v[134:135]
	v_lshl_add_u64 v[128:129], v[128:129], 0, v[130:131]
	v_add_co_u32_e32 v136, vcc, s72, v128
	v_ashrrev_i32_e32 v127, 31, v126
	s_nop 0
	v_addc_co_u32_e32 v137, vcc, 0, v129, vcc
	s_waitcnt vmcnt(0)
	v_lshlrev_b32_e32 v152, 16, v122
	v_and_b32_e32 v153, 0xffff0000, v122
	v_lshlrev_b32_e32 v122, 16, v123
	v_and_b32_e32 v123, 0xffff0000, v123
	v_lshlrev_b32_e32 v154, 16, v124
	v_and_b32_e32 v155, 0xffff0000, v124
	v_lshlrev_b32_e32 v124, 16, v125
	v_and_b32_e32 v125, 0xffff0000, v125
	v_pk_mul_f32 v[120:121], v[120:121], v[122:123]
	v_pk_mul_f32 v[118:119], v[118:119], v[152:153]
	v_pk_mul_f32 v[122:123], v[116:117], v[124:125]
	v_pk_mul_f32 v[116:117], v[114:115], v[154:155]
	v_cvt_pk_bf16_f32 v114, v118, v119
	v_cvt_pk_bf16_f32 v115, v120, v121
	v_cvt_pk_bf16_f32 v116, v116, v117
	v_cvt_pk_bf16_f32 v117, v122, v123
	global_store_dwordx4 v[156:157], v[114:117], off offset:256
	global_load_dwordx4 v[114:117], v[136:137], off
	v_lshlrev_b64 v[118:119], 12, v[126:127]
	v_lshl_add_u64 v[118:119], s[28:29], 0, v[118:119]
	v_lshl_add_u64 v[118:119], v[118:119], 0, v[130:131]
	v_lshl_add_u64 v[120:121], v[128:129], 0, s[34:35]
	s_waitcnt vmcnt(0)
	v_lshlrev_b32_e32 v122, 16, v114
	v_and_b32_e32 v123, 0xffff0000, v114
	v_lshlrev_b32_e32 v114, 16, v115
	v_and_b32_e32 v115, 0xffff0000, v115
	v_lshlrev_b32_e32 v124, 16, v116
	v_and_b32_e32 v125, 0xffff0000, v116
	v_lshlrev_b32_e32 v116, 16, v117
	v_and_b32_e32 v117, 0xffff0000, v117
	v_pk_mul_f32 v[112:113], v[112:113], v[114:115]
	v_pk_mul_f32 v[110:111], v[110:111], v[122:123]
	v_pk_mul_f32 v[114:115], v[108:109], v[116:117]
	v_pk_mul_f32 v[108:109], v[106:107], v[124:125]
	v_cvt_pk_bf16_f32 v106, v110, v111
	v_cvt_pk_bf16_f32 v107, v112, v113
	v_cvt_pk_bf16_f32 v108, v108, v109
	v_cvt_pk_bf16_f32 v109, v114, v115
	global_store_dwordx4 v[118:119], v[106:109], off
	global_load_dwordx4 v[106:109], v[120:121], off offset:256
	v_add_u32_e32 v110, 32, v132
	v_mad_i64_i32 v[112:113], s[0:1], v110, s47, v[134:135]
	v_lshl_add_u64 v[112:113], v[112:113], 0, v[130:131]
	v_add_co_u32_e32 v114, vcc, s72, v112
	v_ashrrev_i32_e32 v111, 31, v110
	s_nop 0
	v_addc_co_u32_e32 v115, vcc, 0, v113, vcc
	s_waitcnt vmcnt(0)
	v_lshlrev_b32_e32 v116, 16, v106
	v_and_b32_e32 v117, 0xffff0000, v106
	v_lshlrev_b32_e32 v106, 16, v107
	v_and_b32_e32 v107, 0xffff0000, v107
	v_lshlrev_b32_e32 v120, 16, v108
	v_and_b32_e32 v121, 0xffff0000, v108
	v_lshlrev_b32_e32 v108, 16, v109
	v_and_b32_e32 v109, 0xffff0000, v109
	v_pk_mul_f32 v[104:105], v[104:105], v[106:107]
	v_pk_mul_f32 v[102:103], v[102:103], v[116:117]
	v_pk_mul_f32 v[106:107], v[100:101], v[108:109]
	v_pk_mul_f32 v[100:101], v[98:99], v[120:121]
	v_cvt_pk_bf16_f32 v98, v102, v103
	v_cvt_pk_bf16_f32 v99, v104, v105
	v_cvt_pk_bf16_f32 v100, v100, v101
	v_cvt_pk_bf16_f32 v101, v106, v107
	global_store_dwordx4 v[118:119], v[98:101], off offset:256
	global_load_dwordx4 v[98:101], v[114:115], off
	v_lshlrev_b64 v[102:103], 12, v[110:111]
	v_lshl_add_u64 v[102:103], s[28:29], 0, v[102:103]
	v_lshl_add_u64 v[102:103], v[102:103], 0, v[130:131]
	v_lshl_add_u64 v[104:105], v[112:113], 0, s[34:35]
	s_waitcnt vmcnt(0)
	v_lshlrev_b32_e32 v106, 16, v98
	v_and_b32_e32 v107, 0xffff0000, v98
	v_lshlrev_b32_e32 v98, 16, v99
	v_and_b32_e32 v99, 0xffff0000, v99
	v_lshlrev_b32_e32 v108, 16, v100
	v_and_b32_e32 v109, 0xffff0000, v100
	v_lshlrev_b32_e32 v100, 16, v101
	v_and_b32_e32 v101, 0xffff0000, v101
	v_pk_mul_f32 v[96:97], v[96:97], v[98:99]
	v_pk_mul_f32 v[94:95], v[94:95], v[106:107]
	v_pk_mul_f32 v[98:99], v[92:93], v[100:101]
	v_pk_mul_f32 v[92:93], v[90:91], v[108:109]
	v_cvt_pk_bf16_f32 v90, v94, v95
	v_cvt_pk_bf16_f32 v91, v96, v97
	v_cvt_pk_bf16_f32 v92, v92, v93
	v_cvt_pk_bf16_f32 v93, v98, v99
	global_store_dwordx4 v[102:103], v[90:93], off
	global_load_dwordx4 v[90:93], v[104:105], off offset:256
	v_add_u32_e32 v94, 48, v132
	v_mad_i64_i32 v[96:97], s[0:1], v94, s47, v[134:135]
	v_lshl_add_u64 v[96:97], v[96:97], 0, v[130:131]
	v_add_co_u32_e32 v98, vcc, s72, v96
	v_ashrrev_i32_e32 v95, 31, v94
	s_nop 0
	v_addc_co_u32_e32 v99, vcc, 0, v97, vcc
	s_waitcnt vmcnt(0)
	v_lshlrev_b32_e32 v100, 16, v90
	v_and_b32_e32 v101, 0xffff0000, v90
	v_lshlrev_b32_e32 v90, 16, v91
	v_and_b32_e32 v91, 0xffff0000, v91
	v_lshlrev_b32_e32 v104, 16, v92
	v_and_b32_e32 v105, 0xffff0000, v92
	v_lshlrev_b32_e32 v92, 16, v93
	v_and_b32_e32 v93, 0xffff0000, v93
	v_pk_mul_f32 v[88:89], v[88:89], v[90:91]
	v_pk_mul_f32 v[86:87], v[86:87], v[100:101]
	v_pk_mul_f32 v[90:91], v[84:85], v[92:93]
	v_pk_mul_f32 v[84:85], v[82:83], v[104:105]
	v_cvt_pk_bf16_f32 v82, v86, v87
	v_cvt_pk_bf16_f32 v83, v88, v89
	v_cvt_pk_bf16_f32 v84, v84, v85
	v_cvt_pk_bf16_f32 v85, v90, v91
	global_store_dwordx4 v[102:103], v[82:85], off offset:256
	global_load_dwordx4 v[82:85], v[98:99], off
	v_lshlrev_b64 v[86:87], 12, v[94:95]
	v_lshl_add_u64 v[86:87], s[28:29], 0, v[86:87]
	v_lshl_add_u64 v[86:87], v[86:87], 0, v[130:131]
	v_lshl_add_u64 v[88:89], v[96:97], 0, s[34:35]
	s_waitcnt vmcnt(0)
	v_lshlrev_b32_e32 v90, 16, v82
	v_and_b32_e32 v91, 0xffff0000, v82
	v_lshlrev_b32_e32 v82, 16, v83
	v_and_b32_e32 v83, 0xffff0000, v83
	v_lshlrev_b32_e32 v92, 16, v84
	v_and_b32_e32 v93, 0xffff0000, v84
	v_lshlrev_b32_e32 v84, 16, v85
	v_and_b32_e32 v85, 0xffff0000, v85
	v_pk_mul_f32 v[80:81], v[80:81], v[82:83]
	v_pk_mul_f32 v[78:79], v[78:79], v[90:91]
	v_pk_mul_f32 v[82:83], v[76:77], v[84:85]
	v_pk_mul_f32 v[76:77], v[74:75], v[92:93]
	v_cvt_pk_bf16_f32 v74, v78, v79
	v_cvt_pk_bf16_f32 v75, v80, v81
	v_cvt_pk_bf16_f32 v76, v76, v77
	v_cvt_pk_bf16_f32 v77, v82, v83
	global_store_dwordx4 v[86:87], v[74:77], off
	global_load_dwordx4 v[74:77], v[88:89], off offset:256
	v_add_u32_e32 v78, 0x80, v132
	v_mad_i64_i32 v[80:81], s[0:1], v78, s47, v[134:135]
	v_lshl_add_u64 v[80:81], v[80:81], 0, v[130:131]
	v_add_co_u32_e32 v82, vcc, s72, v80
	v_ashrrev_i32_e32 v79, 31, v78
	s_nop 0
	v_addc_co_u32_e32 v83, vcc, 0, v81, vcc
	s_waitcnt vmcnt(0)
	v_lshlrev_b32_e32 v84, 16, v74
	v_and_b32_e32 v85, 0xffff0000, v74
	v_lshlrev_b32_e32 v74, 16, v75
	v_and_b32_e32 v75, 0xffff0000, v75
	v_lshlrev_b32_e32 v88, 16, v76
	v_and_b32_e32 v89, 0xffff0000, v76
	v_lshlrev_b32_e32 v76, 16, v77
	v_and_b32_e32 v77, 0xffff0000, v77
	v_pk_mul_f32 v[72:73], v[72:73], v[74:75]
	v_pk_mul_f32 v[70:71], v[70:71], v[84:85]
	v_pk_mul_f32 v[74:75], v[68:69], v[76:77]
	v_pk_mul_f32 v[68:69], v[66:67], v[88:89]
	v_cvt_pk_bf16_f32 v66, v70, v71
	v_cvt_pk_bf16_f32 v67, v72, v73
	v_cvt_pk_bf16_f32 v68, v68, v69
	v_cvt_pk_bf16_f32 v69, v74, v75
	global_store_dwordx4 v[86:87], v[66:69], off offset:256
	global_load_dwordx4 v[66:69], v[82:83], off
	v_lshlrev_b64 v[70:71], 12, v[78:79]
	v_lshl_add_u64 v[70:71], s[28:29], 0, v[70:71]
	v_lshl_add_u64 v[70:71], v[70:71], 0, v[130:131]
	v_lshl_add_u64 v[72:73], v[80:81], 0, s[34:35]
	s_waitcnt vmcnt(0)
	v_lshlrev_b32_e32 v74, 16, v66
	v_and_b32_e32 v75, 0xffff0000, v66
	v_lshlrev_b32_e32 v66, 16, v67
	v_and_b32_e32 v67, 0xffff0000, v67
	v_lshlrev_b32_e32 v76, 16, v68
	v_and_b32_e32 v77, 0xffff0000, v68
	v_lshlrev_b32_e32 v68, 16, v69
	v_and_b32_e32 v69, 0xffff0000, v69
	v_pk_mul_f32 v[64:65], v[64:65], v[66:67]
	v_pk_mul_f32 v[62:63], v[62:63], v[74:75]
	v_pk_mul_f32 v[66:67], v[60:61], v[68:69]
	v_pk_mul_f32 v[60:61], v[58:59], v[76:77]
	v_cvt_pk_bf16_f32 v58, v62, v63
	v_cvt_pk_bf16_f32 v59, v64, v65
	v_cvt_pk_bf16_f32 v60, v60, v61
	v_cvt_pk_bf16_f32 v61, v66, v67
	global_store_dwordx4 v[70:71], v[58:61], off
	global_load_dwordx4 v[58:61], v[72:73], off offset:256
	v_add_u32_e32 v62, 0x90, v132
	v_mad_i64_i32 v[64:65], s[0:1], v62, s47, v[134:135]
	v_lshl_add_u64 v[64:65], v[64:65], 0, v[130:131]
	v_add_co_u32_e32 v66, vcc, s72, v64
	v_ashrrev_i32_e32 v63, 31, v62
	s_nop 0
	v_addc_co_u32_e32 v67, vcc, 0, v65, vcc
	s_waitcnt vmcnt(0)
	v_lshlrev_b32_e32 v68, 16, v58
	v_and_b32_e32 v69, 0xffff0000, v58
	v_lshlrev_b32_e32 v58, 16, v59
	v_and_b32_e32 v59, 0xffff0000, v59
	v_lshlrev_b32_e32 v72, 16, v60
	v_and_b32_e32 v73, 0xffff0000, v60
	v_lshlrev_b32_e32 v60, 16, v61
	v_and_b32_e32 v61, 0xffff0000, v61
	v_pk_mul_f32 v[56:57], v[56:57], v[58:59]
	v_pk_mul_f32 v[54:55], v[54:55], v[68:69]
	v_pk_mul_f32 v[58:59], v[52:53], v[60:61]
	v_pk_mul_f32 v[52:53], v[50:51], v[72:73]
	v_cvt_pk_bf16_f32 v50, v54, v55
	v_cvt_pk_bf16_f32 v51, v56, v57
	v_cvt_pk_bf16_f32 v52, v52, v53
	v_cvt_pk_bf16_f32 v53, v58, v59
	global_store_dwordx4 v[70:71], v[50:53], off offset:256
	global_load_dwordx4 v[50:53], v[66:67], off
	v_lshlrev_b64 v[54:55], 12, v[62:63]
	v_lshl_add_u64 v[54:55], s[28:29], 0, v[54:55]
	v_lshl_add_u64 v[54:55], v[54:55], 0, v[130:131]
	v_lshl_add_u64 v[56:57], v[64:65], 0, s[34:35]
	s_waitcnt vmcnt(0)
	v_lshlrev_b32_e32 v58, 16, v50
	v_and_b32_e32 v59, 0xffff0000, v50
	v_lshlrev_b32_e32 v50, 16, v51
	v_and_b32_e32 v51, 0xffff0000, v51
	v_lshlrev_b32_e32 v60, 16, v52
	v_and_b32_e32 v61, 0xffff0000, v52
	v_lshlrev_b32_e32 v52, 16, v53
	v_and_b32_e32 v53, 0xffff0000, v53
	v_pk_mul_f32 v[48:49], v[48:49], v[50:51]
	v_pk_mul_f32 v[46:47], v[46:47], v[58:59]
	v_pk_mul_f32 v[50:51], v[44:45], v[52:53]
	v_pk_mul_f32 v[44:45], v[42:43], v[60:61]
	v_cvt_pk_bf16_f32 v42, v46, v47
	v_cvt_pk_bf16_f32 v43, v48, v49
	v_cvt_pk_bf16_f32 v44, v44, v45
	v_cvt_pk_bf16_f32 v45, v50, v51
	global_store_dwordx4 v[54:55], v[42:45], off
	global_load_dwordx4 v[42:45], v[56:57], off offset:256
	v_add_u32_e32 v46, 0xa0, v132
	v_mad_i64_i32 v[48:49], s[0:1], v46, s47, v[134:135]
	v_lshl_add_u64 v[48:49], v[48:49], 0, v[130:131]
	v_add_co_u32_e32 v50, vcc, s72, v48
	v_ashrrev_i32_e32 v47, 31, v46
	s_nop 0
	v_addc_co_u32_e32 v51, vcc, 0, v49, vcc
	s_waitcnt vmcnt(0)
	v_lshlrev_b32_e32 v52, 16, v42
	v_and_b32_e32 v53, 0xffff0000, v42
	v_lshlrev_b32_e32 v42, 16, v43
	v_and_b32_e32 v43, 0xffff0000, v43
	v_lshlrev_b32_e32 v56, 16, v44
	v_and_b32_e32 v57, 0xffff0000, v44
	v_lshlrev_b32_e32 v44, 16, v45
	v_and_b32_e32 v45, 0xffff0000, v45
	v_pk_mul_f32 v[40:41], v[40:41], v[42:43]
	v_pk_mul_f32 v[38:39], v[38:39], v[52:53]
	v_pk_mul_f32 v[42:43], v[36:37], v[44:45]
	v_pk_mul_f32 v[36:37], v[34:35], v[56:57]
	v_cvt_pk_bf16_f32 v34, v38, v39
	v_cvt_pk_bf16_f32 v35, v40, v41
	v_cvt_pk_bf16_f32 v36, v36, v37
	v_cvt_pk_bf16_f32 v37, v42, v43
	global_store_dwordx4 v[54:55], v[34:37], off offset:256
	global_load_dwordx4 v[34:37], v[50:51], off
	v_lshlrev_b64 v[38:39], 12, v[46:47]
	v_lshl_add_u64 v[38:39], s[28:29], 0, v[38:39]
	v_lshl_add_u64 v[38:39], v[38:39], 0, v[130:131]
	v_lshl_add_u64 v[40:41], v[48:49], 0, s[34:35]
	s_waitcnt vmcnt(0)
	v_lshlrev_b32_e32 v42, 16, v34
	v_and_b32_e32 v43, 0xffff0000, v34
	v_lshlrev_b32_e32 v34, 16, v35
	v_and_b32_e32 v35, 0xffff0000, v35
	v_lshlrev_b32_e32 v44, 16, v36
	v_and_b32_e32 v45, 0xffff0000, v36
	v_lshlrev_b32_e32 v36, 16, v37
	v_and_b32_e32 v37, 0xffff0000, v37
	v_pk_mul_f32 v[32:33], v[32:33], v[34:35]
	v_pk_mul_f32 v[30:31], v[30:31], v[42:43]
	v_pk_mul_f32 v[34:35], v[28:29], v[36:37]
	v_pk_mul_f32 v[28:29], v[26:27], v[44:45]
	v_cvt_pk_bf16_f32 v26, v30, v31
	v_cvt_pk_bf16_f32 v27, v32, v33
	v_cvt_pk_bf16_f32 v28, v28, v29
	v_cvt_pk_bf16_f32 v29, v34, v35
	global_store_dwordx4 v[38:39], v[26:29], off
	global_load_dwordx4 v[26:29], v[40:41], off offset:256
	v_add_u32_e32 v30, 0xb0, v132
	v_mad_i64_i32 v[32:33], s[0:1], v30, s47, v[134:135]
	v_lshl_add_u64 v[32:33], v[32:33], 0, v[130:131]
	v_add_co_u32_e32 v34, vcc, s72, v32
	v_ashrrev_i32_e32 v31, 31, v30
	s_nop 0
	v_addc_co_u32_e32 v35, vcc, 0, v33, vcc
	s_and_b64 vcc, exec, s[36:37]
	s_waitcnt vmcnt(0)
	v_lshlrev_b32_e32 v36, 16, v26
	v_and_b32_e32 v37, 0xffff0000, v26
	v_lshlrev_b32_e32 v26, 16, v27
	v_and_b32_e32 v27, 0xffff0000, v27
	v_lshlrev_b32_e32 v40, 16, v28
	v_and_b32_e32 v41, 0xffff0000, v28
	v_lshlrev_b32_e32 v28, 16, v29
	v_and_b32_e32 v29, 0xffff0000, v29
	v_pk_mul_f32 v[24:25], v[24:25], v[26:27]
	v_pk_mul_f32 v[22:23], v[22:23], v[36:37]
	v_pk_mul_f32 v[26:27], v[20:21], v[28:29]
	v_pk_mul_f32 v[20:21], v[18:19], v[40:41]
	v_cvt_pk_bf16_f32 v18, v22, v23
	v_cvt_pk_bf16_f32 v19, v24, v25
	v_cvt_pk_bf16_f32 v20, v20, v21
	v_cvt_pk_bf16_f32 v21, v26, v27
	global_store_dwordx4 v[38:39], v[18:21], off offset:256
	global_load_dwordx4 v[18:21], v[34:35], off
	v_lshlrev_b64 v[22:23], 12, v[30:31]
	v_lshl_add_u64 v[22:23], s[28:29], 0, v[22:23]
	v_lshl_add_u64 v[22:23], v[22:23], 0, v[130:131]
	v_lshl_add_u64 v[24:25], v[32:33], 0, s[34:35]
	s_waitcnt vmcnt(0)
	v_lshlrev_b32_e32 v26, 16, v18
	v_and_b32_e32 v27, 0xffff0000, v18
	v_lshlrev_b32_e32 v18, 16, v19
	v_and_b32_e32 v19, 0xffff0000, v19
	v_lshlrev_b32_e32 v28, 16, v20
	v_and_b32_e32 v29, 0xffff0000, v20
	v_lshlrev_b32_e32 v20, 16, v21
	v_and_b32_e32 v21, 0xffff0000, v21
	v_pk_mul_f32 v[16:17], v[16:17], v[18:19]
	v_pk_mul_f32 v[14:15], v[14:15], v[26:27]
	v_pk_mul_f32 v[18:19], v[12:13], v[20:21]
	v_pk_mul_f32 v[12:13], v[10:11], v[28:29]
	v_cvt_pk_bf16_f32 v10, v14, v15
	v_cvt_pk_bf16_f32 v11, v16, v17
	v_cvt_pk_bf16_f32 v12, v12, v13
	v_cvt_pk_bf16_f32 v13, v18, v19
	global_store_dwordx4 v[22:23], v[10:13], off
	global_load_dwordx4 v[10:13], v[24:25], off offset:256
	s_waitcnt vmcnt(0)
	v_lshlrev_b32_e32 v14, 16, v10
	v_and_b32_e32 v15, 0xffff0000, v10
	v_lshlrev_b32_e32 v10, 16, v11
	v_and_b32_e32 v11, 0xffff0000, v11
	v_lshlrev_b32_e32 v16, 16, v12
	v_and_b32_e32 v17, 0xffff0000, v12
	v_lshlrev_b32_e32 v12, 16, v13
	v_and_b32_e32 v13, 0xffff0000, v13
	v_pk_mul_f32 v[8:9], v[8:9], v[10:11]
	v_pk_mul_f32 v[6:7], v[6:7], v[14:15]
	v_pk_mul_f32 v[10:11], v[4:5], v[12:13]
	v_pk_mul_f32 v[4:5], v[2:3], v[16:17]
	v_cvt_pk_bf16_f32 v2, v6, v7
	v_cvt_pk_bf16_f32 v3, v8, v9
	v_cvt_pk_bf16_f32 v4, v4, v5
	v_cvt_pk_bf16_f32 v5, v10, v11
	global_store_dwordx4 v[22:23], v[2:5], off offset:256
	s_cbranch_vccz .LBB0_715
	s_waitcnt vmcnt(0)
	s_cmpk_gt_u32 s97, 0xff
	s_cbranch_scc1 .LBB0_732
	s_barrier

.LBB0_807:
	s_add_u32 s30, s6, s26
	s_addc_u32 s31, s7, s27
	s_add_u32 s30, s30, 0x100
	s_addc_u32 s31, s31, 0
	s_add_u32 s81, s79, s26
	s_addc_u32 s82, s80, s27
	s_add_i32 s83, 0, 0x10000
	ds_read_b128 v[152:155], v224
	ds_read_b128 v[156:159], v224 offset:1024
	ds_read_b128 v[160:163], v224 offset:2048
	ds_read_b128 v[164:167], v224 offset:3072
	s_cmpk_eq_i32 s26, 0xf00
	s_cselect_b32 s41, s23, s31
	s_cselect_b32 s40, s22, s30
	s_cselect_b32 s31, s9, s82
	s_cselect_b32 s30, s44, s81
	v_lshl_add_u64 v[146:147], v[140:141], 0, s[26:27]
	s_add_i32 m0, s61, 0xc000
	ds_read_b128 v[168:171], v145
	ds_read_b128 v[172:175], v145 offset:1024
	ds_read_b128 v[176:179], v145 offset:2048
	ds_read_b128 v[180:183], v145 offset:3072
	ds_read_b128 v[184:187], v145 offset:4096
	ds_read_b128 v[188:191], v145 offset:5120
	ds_read_b128 v[192:195], v145 offset:6144
	ds_read_b128 v[196:199], v145 offset:7168
	global_load_lds_dwordx4 v[146:147], off
	v_lshl_add_u64 v[146:147], v[142:143], 0, s[26:27]
	s_add_i32 m0, s61, 0xe000
	s_nop 0
	global_load_lds_dwordx4 v[146:147], off
	s_waitcnt lgkmcnt(8)
	s_barrier
	s_waitcnt lgkmcnt(7)
	v_mfma_f32_16x16x32_bf16 v[126:129], v[152:155], v[168:171], v[126:129]
	v_mfma_f32_16x16x32_bf16 v[122:125], v[160:163], v[168:171], v[122:125]
	s_waitcnt lgkmcnt(5)
	v_mfma_f32_16x16x32_bf16 v[110:113], v[152:155], v[176:179], v[110:113]
	v_mfma_f32_16x16x32_bf16 v[106:109], v[160:163], v[176:179], v[106:109]
	s_waitcnt lgkmcnt(3)
	v_mfma_f32_16x16x32_bf16 v[94:97], v[152:155], v[184:187], v[94:97]
	v_mfma_f32_16x16x32_bf16 v[90:93], v[160:163], v[184:187], v[90:93]
	s_waitcnt lgkmcnt(1)
	v_mfma_f32_16x16x32_bf16 v[78:81], v[152:155], v[192:195], v[78:81]
	v_mfma_f32_16x16x32_bf16 v[74:77], v[160:163], v[192:195], v[74:77]
	v_mfma_f32_16x16x32_bf16 v[126:129], v[156:159], v[172:175], v[126:129]
	v_mfma_f32_16x16x32_bf16 v[122:125], v[164:167], v[172:175], v[122:125]
	v_mfma_f32_16x16x32_bf16 v[110:113], v[156:159], v[180:183], v[110:113]
	v_mfma_f32_16x16x32_bf16 v[106:109], v[164:167], v[180:183], v[106:109]
	v_mfma_f32_16x16x32_bf16 v[94:97], v[156:159], v[188:191], v[94:97]
	v_mfma_f32_16x16x32_bf16 v[90:93], v[164:167], v[188:191], v[90:93]
	s_waitcnt lgkmcnt(0)
	v_mfma_f32_16x16x32_bf16 v[78:81], v[156:159], v[196:199], v[78:81]
	v_mfma_f32_16x16x32_bf16 v[74:77], v[164:167], v[196:199], v[74:77]
	s_barrier
	s_add_i32 s81, 0, 0x14000
	s_add_i32 s82, s83, s60
	ds_read_b128 v[200:203], v225
	ds_read_b128 v[204:207], v225 offset:1024
	ds_read_b128 v[216:219], v225 offset:2048
	ds_read_b128 v[220:223], v225 offset:3072
	s_mov_b32 m0, s82
	s_nop 0
	global_load_lds_dwordx4 v0, s[30:31]
	s_add_i32 m0, s82, 0x2000
	s_nop 0
	global_load_lds_dwordx4 v134, s[30:31]
	s_barrier
	s_waitcnt lgkmcnt(3)
	v_mfma_f32_16x16x32_bf16 v[118:121], v[200:203], v[168:171], v[118:121]
	s_waitcnt lgkmcnt(1)
	v_mfma_f32_16x16x32_bf16 v[114:117], v[216:219], v[168:171], v[114:117]
	v_mfma_f32_16x16x32_bf16 v[102:105], v[200:203], v[176:179], v[102:105]
	v_mfma_f32_16x16x32_bf16 v[98:101], v[216:219], v[176:179], v[98:101]
	v_mfma_f32_16x16x32_bf16 v[86:89], v[200:203], v[184:187], v[86:89]
	v_mfma_f32_16x16x32_bf16 v[82:85], v[216:219], v[184:187], v[82:85]
	v_mfma_f32_16x16x32_bf16 v[70:73], v[200:203], v[192:195], v[70:73]
	v_mfma_f32_16x16x32_bf16 v[66:69], v[216:219], v[192:195], v[66:69]
	v_mfma_f32_16x16x32_bf16 v[118:121], v[204:207], v[172:175], v[118:121]
	s_waitcnt lgkmcnt(0)
	v_mfma_f32_16x16x32_bf16 v[114:117], v[220:223], v[172:175], v[114:117]
	v_mfma_f32_16x16x32_bf16 v[102:105], v[204:207], v[180:183], v[102:105]
	v_mfma_f32_16x16x32_bf16 v[98:101], v[220:223], v[180:183], v[98:101]
	v_mfma_f32_16x16x32_bf16 v[86:89], v[204:207], v[188:191], v[86:89]
	v_mfma_f32_16x16x32_bf16 v[82:85], v[220:223], v[188:191], v[82:85]
	v_mfma_f32_16x16x32_bf16 v[70:73], v[204:207], v[196:199], v[70:73]
	v_mfma_f32_16x16x32_bf16 v[66:69], v[220:223], v[196:199], v[66:69]
	s_mov_b32 m0, s61
	s_add_u32 s98, s40, 0x80
	s_addc_u32 s99, s41, 0
	s_barrier
	ds_read_b128 v[168:171], v145 offset:16384
	ds_read_b128 v[172:175], v145 offset:17408
	ds_read_b128 v[176:179], v145 offset:18432
	ds_read_b128 v[180:183], v145 offset:19456
	ds_read_b128 v[184:187], v145 offset:20480
	ds_read_b128 v[188:191], v145 offset:21504
	ds_read_b128 v[192:195], v145 offset:22528
	global_load_lds_dwordx4 v0, s[40:41]
	s_mov_b32 m0, s64
	ds_read_b128 v[196:199], v145 offset:23552
	global_load_lds_dwordx4 v134, s[40:41]
	s_barrier
	s_waitcnt lgkmcnt(7)
	v_mfma_f32_16x16x32_bf16 v[62:65], v[152:155], v[168:171], v[62:65]
	v_mfma_f32_16x16x32_bf16 v[58:61], v[160:163], v[168:171], v[58:61]
	s_waitcnt lgkmcnt(5)
	v_mfma_f32_16x16x32_bf16 v[46:49], v[152:155], v[176:179], v[46:49]
	v_mfma_f32_16x16x32_bf16 v[42:45], v[160:163], v[176:179], v[42:45]
	s_waitcnt lgkmcnt(3)
	v_mfma_f32_16x16x32_bf16 v[30:33], v[152:155], v[184:187], v[30:33]
	v_mfma_f32_16x16x32_bf16 v[26:29], v[160:163], v[184:187], v[26:29]
	s_waitcnt lgkmcnt(1)
	v_mfma_f32_16x16x32_bf16 v[14:17], v[152:155], v[192:195], v[14:17]
	v_mfma_f32_16x16x32_bf16 v[10:13], v[160:163], v[192:195], v[10:13]
	v_mfma_f32_16x16x32_bf16 v[62:65], v[156:159], v[172:175], v[62:65]
	v_mfma_f32_16x16x32_bf16 v[58:61], v[164:167], v[172:175], v[58:61]
	v_mfma_f32_16x16x32_bf16 v[46:49], v[156:159], v[180:183], v[46:49]
	v_mfma_f32_16x16x32_bf16 v[42:45], v[164:167], v[180:183], v[42:45]
	v_mfma_f32_16x16x32_bf16 v[30:33], v[156:159], v[188:191], v[30:33]
	v_mfma_f32_16x16x32_bf16 v[26:29], v[164:167], v[188:191], v[26:29]
	s_waitcnt lgkmcnt(0)
	v_mfma_f32_16x16x32_bf16 v[14:17], v[156:159], v[196:199], v[14:17]
	v_mfma_f32_16x16x32_bf16 v[10:13], v[164:167], v[196:199], v[10:13]
	s_barrier
	s_add_i32 s81, s81, s60
	s_mov_b32 m0, s81
	s_add_u32 s82, s30, 0x80000
	s_addc_u32 s83, s31, 0
	global_load_lds_dwordx4 v0, s[82:83]
	s_add_i32 m0, s81, 0x2000
	s_nop 0
	global_load_lds_dwordx4 v134, s[82:83]
	s_waitcnt vmcnt(6)
	s_barrier
	v_mfma_f32_16x16x32_bf16 v[54:57], v[200:203], v[168:171], v[54:57]
	v_mfma_f32_16x16x32_bf16 v[50:53], v[216:219], v[168:171], v[50:53]
	v_mfma_f32_16x16x32_bf16 v[38:41], v[200:203], v[176:179], v[38:41]
	v_mfma_f32_16x16x32_bf16 v[34:37], v[216:219], v[176:179], v[34:37]
	v_mfma_f32_16x16x32_bf16 v[22:25], v[200:203], v[184:187], v[22:25]
	v_mfma_f32_16x16x32_bf16 v[18:21], v[216:219], v[184:187], v[18:21]
	v_mfma_f32_16x16x32_bf16 v[6:9], v[200:203], v[192:195], v[6:9]
	v_mfma_f32_16x16x32_bf16 v[2:5], v[216:219], v[192:195], v[2:5]
	v_mfma_f32_16x16x32_bf16 v[54:57], v[204:207], v[172:175], v[54:57]
	v_mfma_f32_16x16x32_bf16 v[50:53], v[220:223], v[172:175], v[50:53]
	v_mfma_f32_16x16x32_bf16 v[38:41], v[204:207], v[180:183], v[38:41]
	v_mfma_f32_16x16x32_bf16 v[34:37], v[220:223], v[180:183], v[34:37]
	v_mfma_f32_16x16x32_bf16 v[22:25], v[204:207], v[188:191], v[22:25]
	v_mfma_f32_16x16x32_bf16 v[18:21], v[220:223], v[188:191], v[18:21]
	v_mfma_f32_16x16x32_bf16 v[6:9], v[204:207], v[196:199], v[6:9]
	v_mfma_f32_16x16x32_bf16 v[2:5], v[220:223], v[196:199], v[2:5]
	s_add_i32 s81, 0, 0x18000
	s_barrier
	ds_read_b128 v[152:155], v226
	ds_read_b128 v[156:159], v226 offset:1024
	ds_read_b128 v[160:163], v226 offset:2048
	ds_read_b128 v[164:167], v226 offset:3072
	s_add_u32 s40, s40, 0x80000
	s_addc_u32 s41, s41, 0
	s_mov_b32 m0, s67
	ds_read_b128 v[168:171], v145 offset:32768
	ds_read_b128 v[172:175], v145 offset:33792
	ds_read_b128 v[176:179], v145 offset:34816
	ds_read_b128 v[180:183], v145 offset:35840
	ds_read_b128 v[184:187], v145 offset:36864
	ds_read_b128 v[188:191], v145 offset:37888
	ds_read_b128 v[192:195], v145 offset:38912
	global_load_lds_dwordx4 v0, s[40:41]
	s_mov_b32 m0, s68
	ds_read_b128 v[196:199], v145 offset:39936
	global_load_lds_dwordx4 v134, s[40:41]
	s_waitcnt lgkmcnt(8)
	s_barrier
	s_waitcnt lgkmcnt(7)
	v_mfma_f32_16x16x32_bf16 v[126:129], v[152:155], v[168:171], v[126:129]
	v_mfma_f32_16x16x32_bf16 v[122:125], v[160:163], v[168:171], v[122:125]
	s_waitcnt lgkmcnt(5)
	v_mfma_f32_16x16x32_bf16 v[110:113], v[152:155], v[176:179], v[110:113]
	v_mfma_f32_16x16x32_bf16 v[106:109], v[160:163], v[176:179], v[106:109]
	s_waitcnt lgkmcnt(3)
	v_mfma_f32_16x16x32_bf16 v[94:97], v[152:155], v[184:187], v[94:97]
	v_mfma_f32_16x16x32_bf16 v[90:93], v[160:163], v[184:187], v[90:93]
	s_waitcnt lgkmcnt(1)
	v_mfma_f32_16x16x32_bf16 v[78:81], v[152:155], v[192:195], v[78:81]
	v_mfma_f32_16x16x32_bf16 v[74:77], v[160:163], v[192:195], v[74:77]
	v_mfma_f32_16x16x32_bf16 v[126:129], v[156:159], v[172:175], v[126:129]
	v_mfma_f32_16x16x32_bf16 v[122:125], v[164:167], v[172:175], v[122:125]
	v_mfma_f32_16x16x32_bf16 v[110:113], v[156:159], v[180:183], v[110:113]
	v_mfma_f32_16x16x32_bf16 v[106:109], v[164:167], v[180:183], v[106:109]
	v_mfma_f32_16x16x32_bf16 v[94:97], v[156:159], v[188:191], v[94:97]
	v_mfma_f32_16x16x32_bf16 v[90:93], v[164:167], v[188:191], v[90:93]
	s_waitcnt lgkmcnt(0)
	v_mfma_f32_16x16x32_bf16 v[78:81], v[156:159], v[196:199], v[78:81]
	v_mfma_f32_16x16x32_bf16 v[74:77], v[164:167], v[196:199], v[74:77]
	s_barrier
	s_add_i32 s40, 0, 0x1c000
	s_add_i32 s41, s81, s60
	s_add_u32 s100, s30, 0x80
	s_addc_u32 s101, s31, 0
	s_mov_b32 m0, s41
	ds_read_b128 v[200:203], v227
	ds_read_b128 v[204:207], v227 offset:1024
	ds_read_b128 v[216:219], v227 offset:2048
	global_load_lds_dwordx4 v0, s[100:101]
	s_add_i32 m0, s41, 0x2000
	ds_read_b128 v[220:223], v227 offset:3072
	global_load_lds_dwordx4 v134, s[100:101]
	s_barrier
	s_waitcnt lgkmcnt(3)
	v_mfma_f32_16x16x32_bf16 v[118:121], v[200:203], v[168:171], v[118:121]
	s_waitcnt lgkmcnt(1)
	v_mfma_f32_16x16x32_bf16 v[114:117], v[216:219], v[168:171], v[114:117]
	v_mfma_f32_16x16x32_bf16 v[102:105], v[200:203], v[176:179], v[102:105]
	v_mfma_f32_16x16x32_bf16 v[98:101], v[216:219], v[176:179], v[98:101]
	v_mfma_f32_16x16x32_bf16 v[86:89], v[200:203], v[184:187], v[86:89]
	v_mfma_f32_16x16x32_bf16 v[82:85], v[216:219], v[184:187], v[82:85]
	v_mfma_f32_16x16x32_bf16 v[70:73], v[200:203], v[192:195], v[70:73]
	v_mfma_f32_16x16x32_bf16 v[66:69], v[216:219], v[192:195], v[66:69]
	v_mfma_f32_16x16x32_bf16 v[118:121], v[204:207], v[172:175], v[118:121]
	s_waitcnt lgkmcnt(0)
	v_mfma_f32_16x16x32_bf16 v[114:117], v[220:223], v[172:175], v[114:117]
	v_mfma_f32_16x16x32_bf16 v[102:105], v[204:207], v[180:183], v[102:105]
	v_mfma_f32_16x16x32_bf16 v[98:101], v[220:223], v[180:183], v[98:101]
	v_mfma_f32_16x16x32_bf16 v[86:89], v[204:207], v[188:191], v[86:89]
	v_mfma_f32_16x16x32_bf16 v[82:85], v[220:223], v[188:191], v[82:85]
	v_mfma_f32_16x16x32_bf16 v[70:73], v[204:207], v[196:199], v[70:73]
	v_mfma_f32_16x16x32_bf16 v[66:69], v[220:223], v[196:199], v[66:69]
	s_mov_b32 m0, s69
	s_barrier
	ds_read_b128 v[168:171], v145 offset:49152
	ds_read_b128 v[172:175], v145 offset:50176
	ds_read_b128 v[176:179], v145 offset:51200
	ds_read_b128 v[180:183], v145 offset:52224
	ds_read_b128 v[184:187], v145 offset:53248
	ds_read_b128 v[188:191], v145 offset:54272
	ds_read_b128 v[192:195], v145 offset:55296
	global_load_lds_dwordx4 v0, s[98:99]
	s_mov_b32 m0, s75
	ds_read_b128 v[196:199], v145 offset:56320
	global_load_lds_dwordx4 v134, s[98:99]
	s_barrier
	s_waitcnt lgkmcnt(7)
	v_mfma_f32_16x16x32_bf16 v[62:65], v[152:155], v[168:171], v[62:65]
	v_mfma_f32_16x16x32_bf16 v[58:61], v[160:163], v[168:171], v[58:61]
	s_waitcnt lgkmcnt(5)
	v_mfma_f32_16x16x32_bf16 v[46:49], v[152:155], v[176:179], v[46:49]
	v_mfma_f32_16x16x32_bf16 v[42:45], v[160:163], v[176:179], v[42:45]
	s_waitcnt lgkmcnt(3)
	v_mfma_f32_16x16x32_bf16 v[30:33], v[152:155], v[184:187], v[30:33]
	v_mfma_f32_16x16x32_bf16 v[26:29], v[160:163], v[184:187], v[26:29]
	s_waitcnt lgkmcnt(1)
	v_mfma_f32_16x16x32_bf16 v[14:17], v[152:155], v[192:195], v[14:17]
	v_mfma_f32_16x16x32_bf16 v[10:13], v[160:163], v[192:195], v[10:13]
	v_mfma_f32_16x16x32_bf16 v[62:65], v[156:159], v[172:175], v[62:65]
	v_mfma_f32_16x16x32_bf16 v[58:61], v[164:167], v[172:175], v[58:61]
	v_mfma_f32_16x16x32_bf16 v[46:49], v[156:159], v[180:183], v[46:49]
	v_mfma_f32_16x16x32_bf16 v[42:45], v[164:167], v[180:183], v[42:45]
	v_mfma_f32_16x16x32_bf16 v[30:33], v[156:159], v[188:191], v[30:33]
	v_mfma_f32_16x16x32_bf16 v[26:29], v[164:167], v[188:191], v[26:29]
	s_waitcnt lgkmcnt(0)
	v_mfma_f32_16x16x32_bf16 v[14:17], v[156:159], v[196:199], v[14:17]
	v_mfma_f32_16x16x32_bf16 v[10:13], v[164:167], v[196:199], v[10:13]
	s_barrier
	s_add_i32 s40, s40, s60
	s_mov_b32 m0, s40
	s_add_u32 s30, s30, 0x80080
	s_addc_u32 s31, s31, 0
	global_load_lds_dwordx4 v0, s[30:31]
	s_add_i32 m0, s40, 0x2000
	s_nop 0
	global_load_lds_dwordx4 v134, s[30:31]
	s_waitcnt vmcnt(6)
	s_barrier
	v_mfma_f32_16x16x32_bf16 v[54:57], v[200:203], v[168:171], v[54:57]
	v_mfma_f32_16x16x32_bf16 v[50:53], v[216:219], v[168:171], v[50:53]
	v_mfma_f32_16x16x32_bf16 v[38:41], v[200:203], v[176:179], v[38:41]
	v_mfma_f32_16x16x32_bf16 v[34:37], v[216:219], v[176:179], v[34:37]
	v_mfma_f32_16x16x32_bf16 v[22:25], v[200:203], v[184:187], v[22:25]
	v_mfma_f32_16x16x32_bf16 v[18:21], v[216:219], v[184:187], v[18:21]
	v_mfma_f32_16x16x32_bf16 v[6:9], v[200:203], v[192:195], v[6:9]
	v_mfma_f32_16x16x32_bf16 v[2:5], v[216:219], v[192:195], v[2:5]
	v_mfma_f32_16x16x32_bf16 v[54:57], v[204:207], v[172:175], v[54:57]
	v_mfma_f32_16x16x32_bf16 v[50:53], v[220:223], v[172:175], v[50:53]
	v_mfma_f32_16x16x32_bf16 v[38:41], v[204:207], v[180:183], v[38:41]
	v_mfma_f32_16x16x32_bf16 v[34:37], v[220:223], v[180:183], v[34:37]
	v_mfma_f32_16x16x32_bf16 v[22:25], v[204:207], v[188:191], v[22:25]
	v_mfma_f32_16x16x32_bf16 v[18:21], v[220:223], v[188:191], v[18:21]
	v_mfma_f32_16x16x32_bf16 v[6:9], v[204:207], v[196:199], v[6:9]
	v_mfma_f32_16x16x32_bf16 v[2:5], v[220:223], v[196:199], v[2:5]
	s_add_i32 s45, s45, 2
	s_add_u32 s26, s26, 0x100
	s_addc_u32 s27, s27, 0
	s_cmp_gt_u32 s45, 29
	s_barrier
	s_cbranch_scc0 .LBB0_807
	s_add_u32 s26, s79, 0xffffff00
	s_addc_u32 s27, s80, -1
	s_and_b64 vcc, exec, s[42:43]
	s_cbranch_vccnz .LBB0_796
	v_mov_b32_e32 v2, 0
	s_mov_b32 s14, s8
	s_mov_b32 s50, s77
	s_mov_b64 s[6:7], s[22:23]
	s_mov_b32 s76, s78
	v_mov_b32_e32 v3, v2
	v_mov_b32_e32 v4, v2
	v_mov_b32_e32 v5, v2
	v_mov_b32_e32 v6, v2
	v_mov_b32_e32 v7, v2
	v_mov_b32_e32 v8, v2
	v_mov_b32_e32 v9, v2
	v_mov_b32_e32 v18, v2
	v_mov_b32_e32 v19, v2
	v_mov_b32_e32 v20, v2
	v_mov_b32_e32 v21, v2
	v_mov_b32_e32 v22, v2
	v_mov_b32_e32 v23, v2
	v_mov_b32_e32 v24, v2
	v_mov_b32_e32 v25, v2
	v_mov_b32_e32 v34, v2
	v_mov_b32_e32 v35, v2
	v_mov_b32_e32 v36, v2
	v_mov_b32_e32 v37, v2
	v_mov_b32_e32 v38, v2
	v_mov_b32_e32 v39, v2
	v_mov_b32_e32 v40, v2
	v_mov_b32_e32 v41, v2
	v_mov_b32_e32 v50, v2
	v_mov_b32_e32 v51, v2
	v_mov_b32_e32 v52, v2
	v_mov_b32_e32 v53, v2
	v_mov_b32_e32 v54, v2
	v_mov_b32_e32 v55, v2
	v_mov_b32_e32 v56, v2
	v_mov_b32_e32 v57, v2
	v_mov_b32_e32 v10, v2
	v_mov_b32_e32 v11, v2
	v_mov_b32_e32 v12, v2
	v_mov_b32_e32 v13, v2
	v_mov_b32_e32 v14, v2
	v_mov_b32_e32 v15, v2
	v_mov_b32_e32 v16, v2
	v_mov_b32_e32 v17, v2
	v_mov_b32_e32 v26, v2
	v_mov_b32_e32 v27, v2
	v_mov_b32_e32 v28, v2
	v_mov_b32_e32 v29, v2
	v_mov_b32_e32 v30, v2
	v_mov_b32_e32 v31, v2
	v_mov_b32_e32 v32, v2
	v_mov_b32_e32 v33, v2
	v_mov_b32_e32 v42, v2
	v_mov_b32_e32 v43, v2
	v_mov_b32_e32 v44, v2
	v_mov_b32_e32 v45, v2
	v_mov_b32_e32 v46, v2
	v_mov_b32_e32 v47, v2
	v_mov_b32_e32 v48, v2
	v_mov_b32_e32 v49, v2
	v_mov_b32_e32 v58, v2
	v_mov_b32_e32 v59, v2
	v_mov_b32_e32 v60, v2
	v_mov_b32_e32 v61, v2
	v_mov_b32_e32 v62, v2
	v_mov_b32_e32 v63, v2
	v_mov_b32_e32 v64, v2
	v_mov_b32_e32 v65, v2
	v_mov_b32_e32 v66, v2
	v_mov_b32_e32 v67, v2
	v_mov_b32_e32 v68, v2
	v_mov_b32_e32 v69, v2
	v_mov_b32_e32 v70, v2
	v_mov_b32_e32 v71, v2
	v_mov_b32_e32 v72, v2
	v_mov_b32_e32 v73, v2
	v_mov_b32_e32 v82, v2
	v_mov_b32_e32 v83, v2
	v_mov_b32_e32 v84, v2
	v_mov_b32_e32 v85, v2
	v_mov_b32_e32 v86, v2
	v_mov_b32_e32 v87, v2
	v_mov_b32_e32 v88, v2
	v_mov_b32_e32 v89, v2
	v_mov_b32_e32 v98, v2
	v_mov_b32_e32 v99, v2
	v_mov_b32_e32 v100, v2
	v_mov_b32_e32 v101, v2
	v_mov_b32_e32 v102, v2
	v_mov_b32_e32 v103, v2
	v_mov_b32_e32 v104, v2
	v_mov_b32_e32 v105, v2
	v_mov_b32_e32 v114, v2
	v_mov_b32_e32 v115, v2
	v_mov_b32_e32 v116, v2
	v_mov_b32_e32 v117, v2
	v_mov_b32_e32 v118, v2
	v_mov_b32_e32 v119, v2
	v_mov_b32_e32 v120, v2
	v_mov_b32_e32 v121, v2
	v_mov_b32_e32 v74, v2
	v_mov_b32_e32 v75, v2
	v_mov_b32_e32 v76, v2
	v_mov_b32_e32 v77, v2
	v_mov_b32_e32 v78, v2
	v_mov_b32_e32 v79, v2
	v_mov_b32_e32 v80, v2
	v_mov_b32_e32 v81, v2
	v_mov_b32_e32 v90, v2
	v_mov_b32_e32 v91, v2
	v_mov_b32_e32 v92, v2
	v_mov_b32_e32 v93, v2
	v_mov_b32_e32 v94, v2
	v_mov_b32_e32 v95, v2
	v_mov_b32_e32 v96, v2
	v_mov_b32_e32 v97, v2
	v_mov_b32_e32 v106, v2
	v_mov_b32_e32 v107, v2
	v_mov_b32_e32 v108, v2
	v_mov_b32_e32 v109, v2
	v_mov_b32_e32 v110, v2
	v_mov_b32_e32 v111, v2
	v_mov_b32_e32 v112, v2
	v_mov_b32_e32 v113, v2
	v_mov_b32_e32 v122, v2
	v_mov_b32_e32 v123, v2
	v_mov_b32_e32 v124, v2
	v_mov_b32_e32 v125, v2
	v_mov_b32_e32 v126, v2
	v_mov_b32_e32 v127, v2
	v_mov_b32_e32 v128, v2
	v_mov_b32_e32 v129, v2
	s_andn2_b64 vcc, exec, s[0:1]
	s_cbranch_vccnz .LBB0_797

.LBB0_939:
	s_add_u32 s36, s30, 0xfff80080
	s_addc_u32 s37, s31, -1
	s_add_i32 s69, 0, 0x10000
	ds_read_b128 v[142:145], v224
	ds_read_b128 v[152:155], v224 offset:1024
	ds_read_b128 v[156:159], v224 offset:2048
	ds_read_b128 v[160:163], v224 offset:3072
	s_cmp_eq_u32 s68, 28
	s_cselect_b32 s39, s27, s37
	s_cselect_b32 s38, s26, s36
	s_cselect_b32 s37, s23, s67
	s_cselect_b32 s36, s42, s43
	s_add_i32 m0, s41, 0xc000
	ds_read_b128 v[164:167], v141
	ds_read_b128 v[168:171], v141 offset:1024
	ds_read_b128 v[172:175], v141 offset:2048
	ds_read_b128 v[176:179], v141 offset:3072
	ds_read_b128 v[180:183], v141 offset:4096
	ds_read_b128 v[184:187], v141 offset:5120
	ds_read_b128 v[188:191], v141 offset:6144
	global_load_lds_dwordx4 v136, s[30:31]
	s_add_i32 m0, s41, 0xe000
	ds_read_b128 v[192:195], v141 offset:7168
	global_load_lds_dwordx4 v138, s[30:31]
	s_waitcnt lgkmcnt(8)
	s_barrier
	s_waitcnt lgkmcnt(7)
	v_mfma_f32_16x16x32_bf16 v[126:129], v[142:145], v[164:167], v[126:129]
	v_mfma_f32_16x16x32_bf16 v[122:125], v[156:159], v[164:167], v[122:125]
	s_waitcnt lgkmcnt(5)
	v_mfma_f32_16x16x32_bf16 v[118:121], v[142:145], v[172:175], v[118:121]
	v_mfma_f32_16x16x32_bf16 v[114:117], v[156:159], v[172:175], v[114:117]
	s_waitcnt lgkmcnt(3)
	v_mfma_f32_16x16x32_bf16 v[102:105], v[142:145], v[180:183], v[102:105]
	v_mfma_f32_16x16x32_bf16 v[98:101], v[156:159], v[180:183], v[98:101]
	s_waitcnt lgkmcnt(1)
	v_mfma_f32_16x16x32_bf16 v[86:89], v[142:145], v[188:191], v[86:89]
	v_mfma_f32_16x16x32_bf16 v[82:85], v[156:159], v[188:191], v[82:85]
	v_mfma_f32_16x16x32_bf16 v[126:129], v[152:155], v[168:171], v[126:129]
	v_mfma_f32_16x16x32_bf16 v[122:125], v[160:163], v[168:171], v[122:125]
	v_mfma_f32_16x16x32_bf16 v[118:121], v[152:155], v[176:179], v[118:121]
	v_mfma_f32_16x16x32_bf16 v[114:117], v[160:163], v[176:179], v[114:117]
	v_mfma_f32_16x16x32_bf16 v[102:105], v[152:155], v[184:187], v[102:105]
	v_mfma_f32_16x16x32_bf16 v[98:101], v[160:163], v[184:187], v[98:101]
	s_waitcnt lgkmcnt(0)
	v_mfma_f32_16x16x32_bf16 v[86:89], v[152:155], v[192:195], v[86:89]
	v_mfma_f32_16x16x32_bf16 v[82:85], v[160:163], v[192:195], v[82:85]
	s_barrier
	s_add_i32 s75, 0, 0x14000
	s_add_i32 s69, s69, s40
	ds_read_b128 v[196:199], v225
	ds_read_b128 v[200:203], v225 offset:1024
	ds_read_b128 v[204:207], v225 offset:2048
	ds_read_b128 v[216:219], v225 offset:3072
	s_mov_b32 m0, s69
	s_nop 0
	global_load_lds_dwordx4 v0, s[36:37]
	s_add_i32 m0, s69, 0x2000
	s_nop 0
	global_load_lds_dwordx4 v130, s[36:37]
	s_barrier
	s_waitcnt lgkmcnt(3)
	v_mfma_f32_16x16x32_bf16 v[110:113], v[196:199], v[164:167], v[110:113]
	s_waitcnt lgkmcnt(1)
	v_mfma_f32_16x16x32_bf16 v[106:109], v[204:207], v[164:167], v[106:109]
	v_mfma_f32_16x16x32_bf16 v[94:97], v[196:199], v[172:175], v[94:97]
	v_mfma_f32_16x16x32_bf16 v[90:93], v[204:207], v[172:175], v[90:93]
	v_mfma_f32_16x16x32_bf16 v[78:81], v[196:199], v[180:183], v[78:81]
	v_mfma_f32_16x16x32_bf16 v[74:77], v[204:207], v[180:183], v[74:77]
	v_mfma_f32_16x16x32_bf16 v[70:73], v[196:199], v[188:191], v[70:73]
	v_mfma_f32_16x16x32_bf16 v[66:69], v[204:207], v[188:191], v[66:69]
	v_mfma_f32_16x16x32_bf16 v[110:113], v[200:203], v[168:171], v[110:113]
	s_waitcnt lgkmcnt(0)
	v_mfma_f32_16x16x32_bf16 v[106:109], v[216:219], v[168:171], v[106:109]
	v_mfma_f32_16x16x32_bf16 v[94:97], v[200:203], v[176:179], v[94:97]
	v_mfma_f32_16x16x32_bf16 v[90:93], v[216:219], v[176:179], v[90:93]
	v_mfma_f32_16x16x32_bf16 v[78:81], v[200:203], v[184:187], v[78:81]
	v_mfma_f32_16x16x32_bf16 v[74:77], v[216:219], v[184:187], v[74:77]
	v_mfma_f32_16x16x32_bf16 v[70:73], v[200:203], v[192:195], v[70:73]
	v_mfma_f32_16x16x32_bf16 v[66:69], v[216:219], v[192:195], v[66:69]
	s_mov_b32 m0, s41
	s_add_u32 s98, s38, 0x80
	s_addc_u32 s99, s39, 0
	s_barrier
	ds_read_b128 v[164:167], v141 offset:16384
	ds_read_b128 v[168:171], v141 offset:17408
	ds_read_b128 v[172:175], v141 offset:18432
	ds_read_b128 v[176:179], v141 offset:19456
	ds_read_b128 v[180:183], v141 offset:20480
	ds_read_b128 v[184:187], v141 offset:21504
	ds_read_b128 v[188:191], v141 offset:22528
	global_load_lds_dwordx4 v134, s[38:39]
	s_mov_b32 m0, s44
	ds_read_b128 v[192:195], v141 offset:23552
	global_load_lds_dwordx4 v132, s[38:39]
	s_barrier
	s_waitcnt lgkmcnt(7)
	v_mfma_f32_16x16x32_bf16 v[62:65], v[142:145], v[164:167], v[62:65]
	v_mfma_f32_16x16x32_bf16 v[58:61], v[156:159], v[164:167], v[58:61]
	s_waitcnt lgkmcnt(5)
	v_mfma_f32_16x16x32_bf16 v[54:57], v[142:145], v[172:175], v[54:57]
	v_mfma_f32_16x16x32_bf16 v[50:53], v[156:159], v[172:175], v[50:53]
	s_waitcnt lgkmcnt(3)
	v_mfma_f32_16x16x32_bf16 v[38:41], v[142:145], v[180:183], v[38:41]
	v_mfma_f32_16x16x32_bf16 v[34:37], v[156:159], v[180:183], v[34:37]
	s_waitcnt lgkmcnt(1)
	v_mfma_f32_16x16x32_bf16 v[22:25], v[142:145], v[188:191], v[22:25]
	v_mfma_f32_16x16x32_bf16 v[18:21], v[156:159], v[188:191], v[18:21]
	v_mfma_f32_16x16x32_bf16 v[62:65], v[152:155], v[168:171], v[62:65]
	v_mfma_f32_16x16x32_bf16 v[58:61], v[160:163], v[168:171], v[58:61]
	v_mfma_f32_16x16x32_bf16 v[54:57], v[152:155], v[176:179], v[54:57]
	v_mfma_f32_16x16x32_bf16 v[50:53], v[160:163], v[176:179], v[50:53]
	v_mfma_f32_16x16x32_bf16 v[38:41], v[152:155], v[184:187], v[38:41]
	v_mfma_f32_16x16x32_bf16 v[34:37], v[160:163], v[184:187], v[34:37]
	s_waitcnt lgkmcnt(0)
	v_mfma_f32_16x16x32_bf16 v[22:25], v[152:155], v[192:195], v[22:25]
	v_mfma_f32_16x16x32_bf16 v[18:21], v[160:163], v[192:195], v[18:21]
	s_barrier
	s_add_i32 s69, s75, s40
	s_mov_b32 m0, s69
	s_add_u32 s76, s36, 0x80000
	s_addc_u32 s77, s37, 0
	global_load_lds_dwordx4 v0, s[76:77]
	s_add_i32 m0, s69, 0x2000
	s_nop 0
	global_load_lds_dwordx4 v130, s[76:77]
	s_waitcnt vmcnt(6)
	s_barrier
	v_mfma_f32_16x16x32_bf16 v[46:49], v[196:199], v[164:167], v[46:49]
	v_mfma_f32_16x16x32_bf16 v[42:45], v[204:207], v[164:167], v[42:45]
	v_mfma_f32_16x16x32_bf16 v[30:33], v[196:199], v[172:175], v[30:33]
	v_mfma_f32_16x16x32_bf16 v[26:29], v[204:207], v[172:175], v[26:29]
	v_mfma_f32_16x16x32_bf16 v[14:17], v[196:199], v[180:183], v[14:17]
	v_mfma_f32_16x16x32_bf16 v[10:13], v[204:207], v[180:183], v[10:13]
	v_mfma_f32_16x16x32_bf16 v[6:9], v[196:199], v[188:191], v[6:9]
	v_mfma_f32_16x16x32_bf16 v[2:5], v[204:207], v[188:191], v[2:5]
	v_mfma_f32_16x16x32_bf16 v[46:49], v[200:203], v[168:171], v[46:49]
	v_mfma_f32_16x16x32_bf16 v[42:45], v[216:219], v[168:171], v[42:45]
	v_mfma_f32_16x16x32_bf16 v[30:33], v[200:203], v[176:179], v[30:33]
	v_mfma_f32_16x16x32_bf16 v[26:29], v[216:219], v[176:179], v[26:29]
	v_mfma_f32_16x16x32_bf16 v[14:17], v[200:203], v[184:187], v[14:17]
	v_mfma_f32_16x16x32_bf16 v[10:13], v[216:219], v[184:187], v[10:13]
	v_mfma_f32_16x16x32_bf16 v[6:9], v[200:203], v[192:195], v[6:9]
	v_mfma_f32_16x16x32_bf16 v[2:5], v[216:219], v[192:195], v[2:5]
	s_add_i32 s69, 0, 0x18000
	s_barrier
	ds_read_b128 v[142:145], v226
	ds_read_b128 v[152:155], v226 offset:1024
	ds_read_b128 v[156:159], v226 offset:2048
	ds_read_b128 v[160:163], v226 offset:3072
	s_add_u32 s38, s38, 0x80000
	s_addc_u32 s39, s39, 0
	s_mov_b32 m0, s45
	ds_read_b128 v[164:167], v141 offset:32768
	ds_read_b128 v[168:171], v141 offset:33792
	ds_read_b128 v[172:175], v141 offset:34816
	ds_read_b128 v[176:179], v141 offset:35840
	ds_read_b128 v[180:183], v141 offset:36864
	ds_read_b128 v[184:187], v141 offset:37888
	ds_read_b128 v[188:191], v141 offset:38912
	global_load_lds_dwordx4 v134, s[38:39]
	s_mov_b32 m0, s50
	ds_read_b128 v[192:195], v141 offset:39936
	global_load_lds_dwordx4 v132, s[38:39]
	s_waitcnt lgkmcnt(8)
	s_barrier
	s_waitcnt lgkmcnt(7)
	v_mfma_f32_16x16x32_bf16 v[126:129], v[142:145], v[164:167], v[126:129]
	v_mfma_f32_16x16x32_bf16 v[122:125], v[156:159], v[164:167], v[122:125]
	s_waitcnt lgkmcnt(5)
	v_mfma_f32_16x16x32_bf16 v[118:121], v[142:145], v[172:175], v[118:121]
	v_mfma_f32_16x16x32_bf16 v[114:117], v[156:159], v[172:175], v[114:117]
	s_waitcnt lgkmcnt(3)
	v_mfma_f32_16x16x32_bf16 v[102:105], v[142:145], v[180:183], v[102:105]
	v_mfma_f32_16x16x32_bf16 v[98:101], v[156:159], v[180:183], v[98:101]
	s_waitcnt lgkmcnt(1)
	v_mfma_f32_16x16x32_bf16 v[86:89], v[142:145], v[188:191], v[86:89]
	v_mfma_f32_16x16x32_bf16 v[82:85], v[156:159], v[188:191], v[82:85]
	v_mfma_f32_16x16x32_bf16 v[126:129], v[152:155], v[168:171], v[126:129]
	v_mfma_f32_16x16x32_bf16 v[122:125], v[160:163], v[168:171], v[122:125]
	v_mfma_f32_16x16x32_bf16 v[118:121], v[152:155], v[176:179], v[118:121]
	v_mfma_f32_16x16x32_bf16 v[114:117], v[160:163], v[176:179], v[114:117]
	v_mfma_f32_16x16x32_bf16 v[102:105], v[152:155], v[184:187], v[102:105]
	v_mfma_f32_16x16x32_bf16 v[98:101], v[160:163], v[184:187], v[98:101]
	s_waitcnt lgkmcnt(0)
	v_mfma_f32_16x16x32_bf16 v[86:89], v[152:155], v[192:195], v[86:89]
	v_mfma_f32_16x16x32_bf16 v[82:85], v[160:163], v[192:195], v[82:85]
	s_barrier
	s_add_i32 s38, 0, 0x1c000
	s_add_i32 s39, s69, s40
	s_add_u32 s100, s36, 0x80
	s_addc_u32 s101, s37, 0
	s_mov_b32 m0, s39
	ds_read_b128 v[196:199], v227
	ds_read_b128 v[200:203], v227 offset:1024
	ds_read_b128 v[204:207], v227 offset:2048
	global_load_lds_dwordx4 v0, s[100:101]
	s_add_i32 m0, s39, 0x2000
	ds_read_b128 v[216:219], v227 offset:3072
	global_load_lds_dwordx4 v130, s[100:101]
	s_barrier
	s_waitcnt lgkmcnt(3)
	v_mfma_f32_16x16x32_bf16 v[110:113], v[196:199], v[164:167], v[110:113]
	s_waitcnt lgkmcnt(1)
	v_mfma_f32_16x16x32_bf16 v[106:109], v[204:207], v[164:167], v[106:109]
	v_mfma_f32_16x16x32_bf16 v[94:97], v[196:199], v[172:175], v[94:97]
	v_mfma_f32_16x16x32_bf16 v[90:93], v[204:207], v[172:175], v[90:93]
	v_mfma_f32_16x16x32_bf16 v[78:81], v[196:199], v[180:183], v[78:81]
	v_mfma_f32_16x16x32_bf16 v[74:77], v[204:207], v[180:183], v[74:77]
	v_mfma_f32_16x16x32_bf16 v[70:73], v[196:199], v[188:191], v[70:73]
	v_mfma_f32_16x16x32_bf16 v[66:69], v[204:207], v[188:191], v[66:69]
	v_mfma_f32_16x16x32_bf16 v[110:113], v[200:203], v[168:171], v[110:113]
	s_waitcnt lgkmcnt(0)
	v_mfma_f32_16x16x32_bf16 v[106:109], v[216:219], v[168:171], v[106:109]
	v_mfma_f32_16x16x32_bf16 v[94:97], v[200:203], v[176:179], v[94:97]
	v_mfma_f32_16x16x32_bf16 v[90:93], v[216:219], v[176:179], v[90:93]
	v_mfma_f32_16x16x32_bf16 v[78:81], v[200:203], v[184:187], v[78:81]
	v_mfma_f32_16x16x32_bf16 v[74:77], v[216:219], v[184:187], v[74:77]
	v_mfma_f32_16x16x32_bf16 v[70:73], v[200:203], v[192:195], v[70:73]
	v_mfma_f32_16x16x32_bf16 v[66:69], v[216:219], v[192:195], v[66:69]
	s_mov_b32 m0, s52
	s_barrier
	ds_read_b128 v[164:167], v141 offset:49152
	ds_read_b128 v[168:171], v141 offset:50176
	ds_read_b128 v[172:175], v141 offset:51200
	ds_read_b128 v[176:179], v141 offset:52224
	ds_read_b128 v[180:183], v141 offset:53248
	ds_read_b128 v[184:187], v141 offset:54272
	ds_read_b128 v[188:191], v141 offset:55296
	global_load_lds_dwordx4 v134, s[98:99]
	s_mov_b32 m0, s53
	ds_read_b128 v[192:195], v141 offset:56320
	global_load_lds_dwordx4 v132, s[98:99]
	s_barrier
	s_waitcnt lgkmcnt(7)
	v_mfma_f32_16x16x32_bf16 v[62:65], v[142:145], v[164:167], v[62:65]
	v_mfma_f32_16x16x32_bf16 v[58:61], v[156:159], v[164:167], v[58:61]
	s_waitcnt lgkmcnt(5)
	v_mfma_f32_16x16x32_bf16 v[54:57], v[142:145], v[172:175], v[54:57]
	v_mfma_f32_16x16x32_bf16 v[50:53], v[156:159], v[172:175], v[50:53]
	s_waitcnt lgkmcnt(3)
	v_mfma_f32_16x16x32_bf16 v[38:41], v[142:145], v[180:183], v[38:41]
	v_mfma_f32_16x16x32_bf16 v[34:37], v[156:159], v[180:183], v[34:37]
	s_waitcnt lgkmcnt(1)
	v_mfma_f32_16x16x32_bf16 v[22:25], v[142:145], v[188:191], v[22:25]
	v_mfma_f32_16x16x32_bf16 v[18:21], v[156:159], v[188:191], v[18:21]
	v_mfma_f32_16x16x32_bf16 v[62:65], v[152:155], v[168:171], v[62:65]
	v_mfma_f32_16x16x32_bf16 v[58:61], v[160:163], v[168:171], v[58:61]
	v_mfma_f32_16x16x32_bf16 v[54:57], v[152:155], v[176:179], v[54:57]
	v_mfma_f32_16x16x32_bf16 v[50:53], v[160:163], v[176:179], v[50:53]
	v_mfma_f32_16x16x32_bf16 v[38:41], v[152:155], v[184:187], v[38:41]
	v_mfma_f32_16x16x32_bf16 v[34:37], v[160:163], v[184:187], v[34:37]
	s_waitcnt lgkmcnt(0)
	v_mfma_f32_16x16x32_bf16 v[22:25], v[152:155], v[192:195], v[22:25]
	v_mfma_f32_16x16x32_bf16 v[18:21], v[160:163], v[192:195], v[18:21]
	s_barrier
	s_add_i32 s38, s38, s40
	s_mov_b32 m0, s38
	s_add_u32 s36, s36, 0x80080
	s_addc_u32 s37, s37, 0
	global_load_lds_dwordx4 v0, s[36:37]
	s_add_i32 m0, s38, 0x2000
	s_nop 0
	global_load_lds_dwordx4 v130, s[36:37]
	s_waitcnt vmcnt(6)
	s_barrier
	v_mfma_f32_16x16x32_bf16 v[46:49], v[196:199], v[164:167], v[46:49]
	v_mfma_f32_16x16x32_bf16 v[42:45], v[204:207], v[164:167], v[42:45]
	v_mfma_f32_16x16x32_bf16 v[30:33], v[196:199], v[172:175], v[30:33]
	v_mfma_f32_16x16x32_bf16 v[26:29], v[204:207], v[172:175], v[26:29]
	v_mfma_f32_16x16x32_bf16 v[14:17], v[196:199], v[180:183], v[14:17]
	v_mfma_f32_16x16x32_bf16 v[10:13], v[204:207], v[180:183], v[10:13]
	v_mfma_f32_16x16x32_bf16 v[6:9], v[196:199], v[188:191], v[6:9]
	v_mfma_f32_16x16x32_bf16 v[2:5], v[204:207], v[188:191], v[2:5]
	v_mfma_f32_16x16x32_bf16 v[46:49], v[200:203], v[168:171], v[46:49]
	v_mfma_f32_16x16x32_bf16 v[42:45], v[216:219], v[168:171], v[42:45]
	v_mfma_f32_16x16x32_bf16 v[30:33], v[200:203], v[176:179], v[30:33]
	v_mfma_f32_16x16x32_bf16 v[26:29], v[216:219], v[176:179], v[26:29]
	v_mfma_f32_16x16x32_bf16 v[14:17], v[200:203], v[184:187], v[14:17]
	v_mfma_f32_16x16x32_bf16 v[10:13], v[216:219], v[184:187], v[10:13]
	v_mfma_f32_16x16x32_bf16 v[6:9], v[200:203], v[192:195], v[6:9]
	v_mfma_f32_16x16x32_bf16 v[2:5], v[216:219], v[192:195], v[2:5]
	s_add_i32 s68, s68, 2
	s_add_u32 s30, s30, 0x100
	s_addc_u32 s31, s31, 0
	s_add_u32 s43, s43, 0x100
	s_addc_u32 s67, s67, 0
	s_cmp_gt_u32 s68, 29
	s_barrier
	s_cbranch_scc0 .LBB0_939
	s_lshr_b32 s23, s66, 3
	s_mulk_i32 s23, 0x880
	s_lshl_b32 s30, s66, 8
	v_mov_b32_e32 v142, v148
	s_and_b32 s30, s30, 0x700
	s_add_i32 s23, s60, s23
	s_add_i32 s23, s23, s30
	v_and_or_b32 v144, v142, 15, s23
	s_lshl_b32 s23, s65, 8
	v_lshrrev_b32_e32 v142, 1, v142
	v_and_or_b32 v142, v142, 24, s23
	v_or_b32_e32 v142, s51, v142
	v_cvt_pk_bf16_f32 v126, v126, v127
	v_cvt_pk_bf16_f32 v127, v128, v129
	v_cvt_pk_bf16_f32 v128, v122, v123
	v_mov_b64_e32 v[122:123], s[6:7]
	v_ashrrev_i32_e32 v143, 31, v142
	v_cvt_pk_bf16_f32 v70, v70, v71
	v_cvt_pk_bf16_f32 v71, v72, v73
	v_cvt_pk_bf16_f32 v72, v66, v67
	v_add_u32_e32 v66, 0x80, v144
	v_cvt_pk_bf16_f32 v129, v124, v125
	v_mad_i64_i32 v[124:125], s[30:31], v144, s74, v[122:123]
	v_lshlrev_b64 v[142:143], 1, v[142:143]
	v_cvt_pk_bf16_f32 v62, v62, v63
	v_cvt_pk_bf16_f32 v63, v64, v65
	v_cvt_pk_bf16_f32 v64, v58, v59
	v_mad_i64_i32 v[58:59], s[30:31], v66, s74, v[122:123]
	v_lshl_add_u64 v[124:125], v[124:125], 0, v[142:143]
	v_cvt_pk_bf16_f32 v110, v110, v111
	v_cvt_pk_bf16_f32 v111, v112, v113
	v_cvt_pk_bf16_f32 v112, v106, v107
	v_cvt_pk_bf16_f32 v113, v108, v109
	v_lshl_add_u64 v[58:59], v[58:59], 0, v[142:143]
	v_cvt_pk_bf16_f32 v46, v46, v47
	v_cvt_pk_bf16_f32 v47, v48, v49
	v_cvt_pk_bf16_f32 v48, v42, v43
	v_cvt_pk_bf16_f32 v49, v44, v45
	global_store_dwordx4 v[124:125], v[110:113], off offset:256
	global_store_dwordx4 v[58:59], v[46:49], off offset:256
	v_cvt_pk_bf16_f32 v94, v94, v95
	v_add_u32_e32 v110, 16, v144
	v_add_u32_e32 v46, 0x90, v144
	v_mad_i64_i32 v[110:111], s[30:31], v110, s74, v[122:123]
	v_mad_i64_i32 v[46:47], s[30:31], v46, s74, v[122:123]
	v_lshl_add_u64 v[110:111], v[110:111], 0, v[142:143]
	v_cvt_pk_bf16_f32 v95, v96, v97
	v_cvt_pk_bf16_f32 v96, v90, v91
	v_cvt_pk_bf16_f32 v97, v92, v93
	v_lshl_add_u64 v[46:47], v[46:47], 0, v[142:143]
	v_cvt_pk_bf16_f32 v30, v30, v31
	v_cvt_pk_bf16_f32 v31, v32, v33
	v_cvt_pk_bf16_f32 v32, v26, v27
	v_cvt_pk_bf16_f32 v33, v28, v29
	global_store_dwordx4 v[110:111], v[94:97], off offset:256
	global_store_dwordx4 v[46:47], v[30:33], off offset:256
	v_cvt_pk_bf16_f32 v78, v78, v79
	v_add_u32_e32 v94, 32, v144
	v_add_u32_e32 v30, 0xa0, v144
	v_mad_i64_i32 v[94:95], s[30:31], v94, s74, v[122:123]
	v_mad_i64_i32 v[30:31], s[30:31], v30, s74, v[122:123]
	v_lshl_add_u64 v[94:95], v[94:95], 0, v[142:143]
	v_cvt_pk_bf16_f32 v79, v80, v81
	v_cvt_pk_bf16_f32 v80, v74, v75
	v_cvt_pk_bf16_f32 v81, v76, v77
	v_lshl_add_u64 v[30:31], v[30:31], 0, v[142:143]
	v_cvt_pk_bf16_f32 v14, v14, v15
	v_cvt_pk_bf16_f32 v15, v16, v17
	v_cvt_pk_bf16_f32 v16, v10, v11
	v_cvt_pk_bf16_f32 v17, v12, v13
	global_store_dwordx4 v[94:95], v[78:81], off offset:256
	global_store_dwordx4 v[30:31], v[14:17], off offset:256
	v_cvt_pk_bf16_f32 v106, v118, v119
	v_add_u32_e32 v78, 48, v144
	v_add_u32_e32 v14, 0xb0, v144
	v_mad_i64_i32 v[78:79], s[30:31], v78, s74, v[122:123]
	v_mad_i64_i32 v[14:15], s[30:31], v14, s74, v[122:123]
	v_cvt_pk_bf16_f32 v107, v120, v121
	v_cvt_pk_bf16_f32 v108, v114, v115
	v_cvt_pk_bf16_f32 v109, v116, v117
	v_cvt_pk_bf16_f32 v90, v102, v103
	v_cvt_pk_bf16_f32 v91, v104, v105
	v_cvt_pk_bf16_f32 v92, v98, v99
	v_cvt_pk_bf16_f32 v93, v100, v101
	v_cvt_pk_bf16_f32 v74, v86, v87
	v_cvt_pk_bf16_f32 v75, v88, v89
	v_cvt_pk_bf16_f32 v76, v82, v83
	v_cvt_pk_bf16_f32 v77, v84, v85
	v_lshl_add_u64 v[78:79], v[78:79], 0, v[142:143]
	v_cvt_pk_bf16_f32 v73, v68, v69
	v_cvt_pk_bf16_f32 v65, v60, v61
	v_cvt_pk_bf16_f32 v42, v54, v55
	v_cvt_pk_bf16_f32 v43, v56, v57
	v_cvt_pk_bf16_f32 v44, v50, v51
	v_cvt_pk_bf16_f32 v45, v52, v53
	v_cvt_pk_bf16_f32 v26, v38, v39
	v_cvt_pk_bf16_f32 v27, v40, v41
	v_cvt_pk_bf16_f32 v28, v34, v35
	v_cvt_pk_bf16_f32 v29, v36, v37
	v_cvt_pk_bf16_f32 v10, v22, v23
	v_cvt_pk_bf16_f32 v11, v24, v25
	v_cvt_pk_bf16_f32 v12, v18, v19
	v_cvt_pk_bf16_f32 v13, v20, v21
	v_lshl_add_u64 v[14:15], v[14:15], 0, v[142:143]
	v_cvt_pk_bf16_f32 v6, v6, v7
	v_cvt_pk_bf16_f32 v7, v8, v9
	v_cvt_pk_bf16_f32 v8, v2, v3
	v_cvt_pk_bf16_f32 v9, v4, v5
	s_and_b64 vcc, exec, s[0:1]
	s_mov_b32 s65, s22
	s_mov_b32 s66, s64
	s_mov_b64 s[36:37], s[28:29]
	s_mov_b64 s[30:31], s[26:27]
	global_store_dwordx4 v[124:125], v[126:129], off
	global_store_dwordx4 v[110:111], v[106:109], off
	global_store_dwordx4 v[94:95], v[90:93], off
	global_store_dwordx4 v[78:79], v[74:77], off
	global_store_dwordx4 v[78:79], v[70:73], off offset:256
	global_store_dwordx4 v[58:59], v[62:65], off
	global_store_dwordx4 v[46:47], v[42:45], off
	global_store_dwordx4 v[30:31], v[26:29], off
	global_store_dwordx4 v[14:15], v[10:13], off
	global_store_dwordx4 v[14:15], v[6:9], off offset:256
	s_cbranch_vccz .LBB0_934
	s_waitcnt vmcnt(0)
	s_cmpk_gt_u32 s14, 0xff
	s_cbranch_scc1 .LBB0_943
	s_barrier

.LBB0_1084:
	s_add_u32 s30, s6, s22
	s_addc_u32 s31, s7, s23
	s_add_u32 s30, s30, 0x100
	s_addc_u32 s31, s31, 0
	s_add_u32 s79, s42, s22
	s_addc_u32 s80, s43, s23
	s_add_i32 s81, 0, 0x10000
	ds_read_b128 v[152:155], v224
	ds_read_b128 v[156:159], v224 offset:1024
	ds_read_b128 v[160:163], v224 offset:2048
	ds_read_b128 v[164:167], v224 offset:3072
	s_cmpk_eq_i32 s22, 0x2a00
	s_cselect_b32 s41, s13, s31
	s_cselect_b32 s40, s12, s30
	s_cselect_b32 s31, s9, s80
	s_cselect_b32 s30, s8, s79
	v_lshl_add_u64 v[200:201], v[142:143], 0, s[22:23]
	s_add_i32 m0, s53, 0xc000
	ds_read_b128 v[168:171], v147
	ds_read_b128 v[172:175], v147 offset:1024
	ds_read_b128 v[176:179], v147 offset:2048
	ds_read_b128 v[180:183], v147 offset:3072
	ds_read_b128 v[184:187], v147 offset:4096
	ds_read_b128 v[188:191], v147 offset:5120
	ds_read_b128 v[192:195], v147 offset:6144
	ds_read_b128 v[196:199], v147 offset:7168
	global_load_lds_dwordx4 v[200:201], off
	v_lshl_add_u64 v[200:201], v[144:145], 0, s[22:23]
	s_add_i32 m0, s53, 0xe000
	s_nop 0
	global_load_lds_dwordx4 v[200:201], off
	s_waitcnt lgkmcnt(8)
	s_barrier
	s_waitcnt lgkmcnt(7)
	v_mfma_f32_16x16x32_bf16 v[126:129], v[152:155], v[168:171], v[126:129]
	v_mfma_f32_16x16x32_bf16 v[122:125], v[160:163], v[168:171], v[122:125]
	s_waitcnt lgkmcnt(5)
	v_mfma_f32_16x16x32_bf16 v[110:113], v[152:155], v[176:179], v[110:113]
	v_mfma_f32_16x16x32_bf16 v[106:109], v[160:163], v[176:179], v[106:109]
	s_waitcnt lgkmcnt(3)
	v_mfma_f32_16x16x32_bf16 v[94:97], v[152:155], v[184:187], v[94:97]
	v_mfma_f32_16x16x32_bf16 v[90:93], v[160:163], v[184:187], v[90:93]
	s_waitcnt lgkmcnt(1)
	v_mfma_f32_16x16x32_bf16 v[78:81], v[152:155], v[192:195], v[78:81]
	v_mfma_f32_16x16x32_bf16 v[74:77], v[160:163], v[192:195], v[74:77]
	v_mfma_f32_16x16x32_bf16 v[126:129], v[156:159], v[172:175], v[126:129]
	v_mfma_f32_16x16x32_bf16 v[122:125], v[164:167], v[172:175], v[122:125]
	v_mfma_f32_16x16x32_bf16 v[110:113], v[156:159], v[180:183], v[110:113]
	v_mfma_f32_16x16x32_bf16 v[106:109], v[164:167], v[180:183], v[106:109]
	v_mfma_f32_16x16x32_bf16 v[94:97], v[156:159], v[188:191], v[94:97]
	v_mfma_f32_16x16x32_bf16 v[90:93], v[164:167], v[188:191], v[90:93]
	s_waitcnt lgkmcnt(0)
	v_mfma_f32_16x16x32_bf16 v[78:81], v[156:159], v[196:199], v[78:81]
	v_mfma_f32_16x16x32_bf16 v[74:77], v[164:167], v[196:199], v[74:77]
	s_barrier
	s_add_i32 s79, 0, 0x14000
	s_add_i32 s80, s81, s52
	s_mov_b32 m0, s80
	ds_read_b128 v[200:203], v225
	ds_read_b128 v[204:207], v225 offset:1024
	ds_read_b128 v[216:219], v225 offset:2048
	global_load_lds_dwordx4 v0, s[30:31]
	s_add_i32 m0, s80, 0x2000
	ds_read_b128 v[220:223], v225 offset:3072
	global_load_lds_dwordx4 v136, s[30:31]
	s_barrier
	s_waitcnt lgkmcnt(3)
	v_mfma_f32_16x16x32_bf16 v[118:121], v[200:203], v[168:171], v[118:121]
	s_waitcnt lgkmcnt(1)
	v_mfma_f32_16x16x32_bf16 v[114:117], v[216:219], v[168:171], v[114:117]
	v_mfma_f32_16x16x32_bf16 v[102:105], v[200:203], v[176:179], v[102:105]
	v_mfma_f32_16x16x32_bf16 v[98:101], v[216:219], v[176:179], v[98:101]
	v_mfma_f32_16x16x32_bf16 v[86:89], v[200:203], v[184:187], v[86:89]
	v_mfma_f32_16x16x32_bf16 v[82:85], v[216:219], v[184:187], v[82:85]
	v_mfma_f32_16x16x32_bf16 v[70:73], v[200:203], v[192:195], v[70:73]
	v_mfma_f32_16x16x32_bf16 v[66:69], v[216:219], v[192:195], v[66:69]
	v_mfma_f32_16x16x32_bf16 v[118:121], v[204:207], v[172:175], v[118:121]
	s_waitcnt lgkmcnt(0)
	v_mfma_f32_16x16x32_bf16 v[114:117], v[220:223], v[172:175], v[114:117]
	v_mfma_f32_16x16x32_bf16 v[102:105], v[204:207], v[180:183], v[102:105]
	v_mfma_f32_16x16x32_bf16 v[98:101], v[220:223], v[180:183], v[98:101]
	v_mfma_f32_16x16x32_bf16 v[86:89], v[204:207], v[188:191], v[86:89]
	v_mfma_f32_16x16x32_bf16 v[82:85], v[220:223], v[188:191], v[82:85]
	v_mfma_f32_16x16x32_bf16 v[70:73], v[204:207], v[196:199], v[70:73]
	v_mfma_f32_16x16x32_bf16 v[66:69], v[220:223], v[196:199], v[66:69]
	s_mov_b32 m0, s53
	s_add_u32 s98, s40, 0x80
	s_addc_u32 s99, s41, 0
	s_barrier
	ds_read_b128 v[168:171], v147 offset:16384
	ds_read_b128 v[172:175], v147 offset:17408
	ds_read_b128 v[176:179], v147 offset:18432
	ds_read_b128 v[180:183], v147 offset:19456
	ds_read_b128 v[184:187], v147 offset:20480
	ds_read_b128 v[188:191], v147 offset:21504
	ds_read_b128 v[192:195], v147 offset:22528
	global_load_lds_dwordx4 v0, s[40:41]
	s_mov_b32 m0, s60
	ds_read_b128 v[196:199], v147 offset:23552
	global_load_lds_dwordx4 v136, s[40:41]
	s_barrier
	s_waitcnt lgkmcnt(7)
	v_mfma_f32_16x16x32_bf16 v[62:65], v[152:155], v[168:171], v[62:65]
	v_mfma_f32_16x16x32_bf16 v[58:61], v[160:163], v[168:171], v[58:61]
	s_waitcnt lgkmcnt(5)
	v_mfma_f32_16x16x32_bf16 v[46:49], v[152:155], v[176:179], v[46:49]
	v_mfma_f32_16x16x32_bf16 v[42:45], v[160:163], v[176:179], v[42:45]
	s_waitcnt lgkmcnt(3)
	v_mfma_f32_16x16x32_bf16 v[30:33], v[152:155], v[184:187], v[30:33]
	v_mfma_f32_16x16x32_bf16 v[26:29], v[160:163], v[184:187], v[26:29]
	s_waitcnt lgkmcnt(1)
	v_mfma_f32_16x16x32_bf16 v[14:17], v[152:155], v[192:195], v[14:17]
	v_mfma_f32_16x16x32_bf16 v[10:13], v[160:163], v[192:195], v[10:13]
	v_mfma_f32_16x16x32_bf16 v[62:65], v[156:159], v[172:175], v[62:65]
	v_mfma_f32_16x16x32_bf16 v[58:61], v[164:167], v[172:175], v[58:61]
	v_mfma_f32_16x16x32_bf16 v[46:49], v[156:159], v[180:183], v[46:49]
	v_mfma_f32_16x16x32_bf16 v[42:45], v[164:167], v[180:183], v[42:45]
	v_mfma_f32_16x16x32_bf16 v[30:33], v[156:159], v[188:191], v[30:33]
	v_mfma_f32_16x16x32_bf16 v[26:29], v[164:167], v[188:191], v[26:29]
	s_waitcnt lgkmcnt(0)
	v_mfma_f32_16x16x32_bf16 v[14:17], v[156:159], v[196:199], v[14:17]
	v_mfma_f32_16x16x32_bf16 v[10:13], v[164:167], v[196:199], v[10:13]
	s_barrier
	s_add_i32 s79, s79, s52
	s_mov_b32 m0, s79
	s_add_u32 s80, s30, 0x158000
	s_addc_u32 s81, s31, 0
	global_load_lds_dwordx4 v0, s[80:81]
	s_add_i32 m0, s79, 0x2000
	s_nop 0
	global_load_lds_dwordx4 v136, s[80:81]
	s_waitcnt vmcnt(6)
	s_barrier
	v_mfma_f32_16x16x32_bf16 v[54:57], v[200:203], v[168:171], v[54:57]
	v_mfma_f32_16x16x32_bf16 v[50:53], v[216:219], v[168:171], v[50:53]
	v_mfma_f32_16x16x32_bf16 v[38:41], v[200:203], v[176:179], v[38:41]
	v_mfma_f32_16x16x32_bf16 v[34:37], v[216:219], v[176:179], v[34:37]
	v_mfma_f32_16x16x32_bf16 v[22:25], v[200:203], v[184:187], v[22:25]
	v_mfma_f32_16x16x32_bf16 v[18:21], v[216:219], v[184:187], v[18:21]
	v_mfma_f32_16x16x32_bf16 v[6:9], v[200:203], v[192:195], v[6:9]
	v_mfma_f32_16x16x32_bf16 v[2:5], v[216:219], v[192:195], v[2:5]
	v_mfma_f32_16x16x32_bf16 v[54:57], v[204:207], v[172:175], v[54:57]
	v_mfma_f32_16x16x32_bf16 v[50:53], v[220:223], v[172:175], v[50:53]
	v_mfma_f32_16x16x32_bf16 v[38:41], v[204:207], v[180:183], v[38:41]
	v_mfma_f32_16x16x32_bf16 v[34:37], v[220:223], v[180:183], v[34:37]
	v_mfma_f32_16x16x32_bf16 v[22:25], v[204:207], v[188:191], v[22:25]
	v_mfma_f32_16x16x32_bf16 v[18:21], v[220:223], v[188:191], v[18:21]
	v_mfma_f32_16x16x32_bf16 v[6:9], v[204:207], v[196:199], v[6:9]
	v_mfma_f32_16x16x32_bf16 v[2:5], v[220:223], v[196:199], v[2:5]
	s_add_i32 s79, 0, 0x18000
	s_barrier
	ds_read_b128 v[152:155], v226
	ds_read_b128 v[156:159], v226 offset:1024
	ds_read_b128 v[160:163], v226 offset:2048
	ds_read_b128 v[164:167], v226 offset:3072
	s_add_u32 s40, s40, 0x158000
	s_addc_u32 s41, s41, 0
	s_mov_b32 m0, s65
	ds_read_b128 v[168:171], v147 offset:32768
	ds_read_b128 v[172:175], v147 offset:33792
	ds_read_b128 v[176:179], v147 offset:34816
	ds_read_b128 v[180:183], v147 offset:35840
	ds_read_b128 v[184:187], v147 offset:36864
	ds_read_b128 v[188:191], v147 offset:37888
	ds_read_b128 v[192:195], v147 offset:38912
	global_load_lds_dwordx4 v0, s[40:41]
	s_mov_b32 m0, s66
	ds_read_b128 v[196:199], v147 offset:39936
	global_load_lds_dwordx4 v136, s[40:41]
	s_waitcnt lgkmcnt(8)
	s_barrier
	s_waitcnt lgkmcnt(7)
	v_mfma_f32_16x16x32_bf16 v[126:129], v[152:155], v[168:171], v[126:129]
	v_mfma_f32_16x16x32_bf16 v[122:125], v[160:163], v[168:171], v[122:125]
	s_waitcnt lgkmcnt(5)
	v_mfma_f32_16x16x32_bf16 v[110:113], v[152:155], v[176:179], v[110:113]
	v_mfma_f32_16x16x32_bf16 v[106:109], v[160:163], v[176:179], v[106:109]
	s_waitcnt lgkmcnt(3)
	v_mfma_f32_16x16x32_bf16 v[94:97], v[152:155], v[184:187], v[94:97]
	v_mfma_f32_16x16x32_bf16 v[90:93], v[160:163], v[184:187], v[90:93]
	s_waitcnt lgkmcnt(1)
	v_mfma_f32_16x16x32_bf16 v[78:81], v[152:155], v[192:195], v[78:81]
	v_mfma_f32_16x16x32_bf16 v[74:77], v[160:163], v[192:195], v[74:77]
	v_mfma_f32_16x16x32_bf16 v[126:129], v[156:159], v[172:175], v[126:129]
	v_mfma_f32_16x16x32_bf16 v[122:125], v[164:167], v[172:175], v[122:125]
	v_mfma_f32_16x16x32_bf16 v[110:113], v[156:159], v[180:183], v[110:113]
	v_mfma_f32_16x16x32_bf16 v[106:109], v[164:167], v[180:183], v[106:109]
	v_mfma_f32_16x16x32_bf16 v[94:97], v[156:159], v[188:191], v[94:97]
	v_mfma_f32_16x16x32_bf16 v[90:93], v[164:167], v[188:191], v[90:93]
	s_waitcnt lgkmcnt(0)
	v_mfma_f32_16x16x32_bf16 v[78:81], v[156:159], v[196:199], v[78:81]
	v_mfma_f32_16x16x32_bf16 v[74:77], v[164:167], v[196:199], v[74:77]
	s_barrier
	s_add_i32 s40, 0, 0x1c000
	s_add_i32 s41, s79, s52
	s_add_u32 s100, s30, 0x80
	s_addc_u32 s101, s31, 0
	s_mov_b32 m0, s41
	ds_read_b128 v[200:203], v227
	ds_read_b128 v[204:207], v227 offset:1024
	ds_read_b128 v[216:219], v227 offset:2048
	global_load_lds_dwordx4 v0, s[100:101]
	s_add_i32 m0, s41, 0x2000
	ds_read_b128 v[220:223], v227 offset:3072
	global_load_lds_dwordx4 v136, s[100:101]
	s_barrier
	s_waitcnt lgkmcnt(3)
	v_mfma_f32_16x16x32_bf16 v[118:121], v[200:203], v[168:171], v[118:121]
	s_waitcnt lgkmcnt(1)
	v_mfma_f32_16x16x32_bf16 v[114:117], v[216:219], v[168:171], v[114:117]
	v_mfma_f32_16x16x32_bf16 v[102:105], v[200:203], v[176:179], v[102:105]
	v_mfma_f32_16x16x32_bf16 v[98:101], v[216:219], v[176:179], v[98:101]
	v_mfma_f32_16x16x32_bf16 v[86:89], v[200:203], v[184:187], v[86:89]
	v_mfma_f32_16x16x32_bf16 v[82:85], v[216:219], v[184:187], v[82:85]
	v_mfma_f32_16x16x32_bf16 v[70:73], v[200:203], v[192:195], v[70:73]
	v_mfma_f32_16x16x32_bf16 v[66:69], v[216:219], v[192:195], v[66:69]
	v_mfma_f32_16x16x32_bf16 v[118:121], v[204:207], v[172:175], v[118:121]
	s_waitcnt lgkmcnt(0)
	v_mfma_f32_16x16x32_bf16 v[114:117], v[220:223], v[172:175], v[114:117]
	v_mfma_f32_16x16x32_bf16 v[102:105], v[204:207], v[180:183], v[102:105]
	v_mfma_f32_16x16x32_bf16 v[98:101], v[220:223], v[180:183], v[98:101]
	v_mfma_f32_16x16x32_bf16 v[86:89], v[204:207], v[188:191], v[86:89]
	v_mfma_f32_16x16x32_bf16 v[82:85], v[220:223], v[188:191], v[82:85]
	v_mfma_f32_16x16x32_bf16 v[70:73], v[204:207], v[196:199], v[70:73]
	v_mfma_f32_16x16x32_bf16 v[66:69], v[220:223], v[196:199], v[66:69]
	s_mov_b32 m0, s67
	s_barrier
	ds_read_b128 v[168:171], v147 offset:49152
	ds_read_b128 v[172:175], v147 offset:50176
	ds_read_b128 v[176:179], v147 offset:51200
	ds_read_b128 v[180:183], v147 offset:52224
	ds_read_b128 v[184:187], v147 offset:53248
	ds_read_b128 v[188:191], v147 offset:54272
	ds_read_b128 v[192:195], v147 offset:55296
	global_load_lds_dwordx4 v0, s[98:99]
	s_mov_b32 m0, s68
	ds_read_b128 v[196:199], v147 offset:56320
	global_load_lds_dwordx4 v136, s[98:99]
	s_barrier
	s_waitcnt lgkmcnt(7)
	v_mfma_f32_16x16x32_bf16 v[62:65], v[152:155], v[168:171], v[62:65]
	v_mfma_f32_16x16x32_bf16 v[58:61], v[160:163], v[168:171], v[58:61]
	s_waitcnt lgkmcnt(5)
	v_mfma_f32_16x16x32_bf16 v[46:49], v[152:155], v[176:179], v[46:49]
	v_mfma_f32_16x16x32_bf16 v[42:45], v[160:163], v[176:179], v[42:45]
	s_waitcnt lgkmcnt(3)
	v_mfma_f32_16x16x32_bf16 v[30:33], v[152:155], v[184:187], v[30:33]
	v_mfma_f32_16x16x32_bf16 v[26:29], v[160:163], v[184:187], v[26:29]
	s_waitcnt lgkmcnt(1)
	v_mfma_f32_16x16x32_bf16 v[14:17], v[152:155], v[192:195], v[14:17]
	v_mfma_f32_16x16x32_bf16 v[10:13], v[160:163], v[192:195], v[10:13]
	v_mfma_f32_16x16x32_bf16 v[62:65], v[156:159], v[172:175], v[62:65]
	v_mfma_f32_16x16x32_bf16 v[58:61], v[164:167], v[172:175], v[58:61]
	v_mfma_f32_16x16x32_bf16 v[46:49], v[156:159], v[180:183], v[46:49]
	v_mfma_f32_16x16x32_bf16 v[42:45], v[164:167], v[180:183], v[42:45]
	v_mfma_f32_16x16x32_bf16 v[30:33], v[156:159], v[188:191], v[30:33]
	v_mfma_f32_16x16x32_bf16 v[26:29], v[164:167], v[188:191], v[26:29]
	s_waitcnt lgkmcnt(0)
	v_mfma_f32_16x16x32_bf16 v[14:17], v[156:159], v[196:199], v[14:17]
	v_mfma_f32_16x16x32_bf16 v[10:13], v[164:167], v[196:199], v[10:13]
	s_barrier
	s_add_i32 s40, s40, s52
	s_mov_b32 m0, s40
	s_add_u32 s30, s30, 0x158080
	s_addc_u32 s31, s31, 0
	global_load_lds_dwordx4 v0, s[30:31]
	s_add_i32 m0, s40, 0x2000
	s_nop 0
	global_load_lds_dwordx4 v136, s[30:31]
	s_waitcnt vmcnt(6)
	s_barrier
	v_mfma_f32_16x16x32_bf16 v[54:57], v[200:203], v[168:171], v[54:57]
	v_mfma_f32_16x16x32_bf16 v[50:53], v[216:219], v[168:171], v[50:53]
	v_mfma_f32_16x16x32_bf16 v[38:41], v[200:203], v[176:179], v[38:41]
	v_mfma_f32_16x16x32_bf16 v[34:37], v[216:219], v[176:179], v[34:37]
	v_mfma_f32_16x16x32_bf16 v[22:25], v[200:203], v[184:187], v[22:25]
	v_mfma_f32_16x16x32_bf16 v[18:21], v[216:219], v[184:187], v[18:21]
	v_mfma_f32_16x16x32_bf16 v[6:9], v[200:203], v[192:195], v[6:9]
	v_mfma_f32_16x16x32_bf16 v[2:5], v[216:219], v[192:195], v[2:5]
	v_mfma_f32_16x16x32_bf16 v[54:57], v[204:207], v[172:175], v[54:57]
	v_mfma_f32_16x16x32_bf16 v[50:53], v[220:223], v[172:175], v[50:53]
	v_mfma_f32_16x16x32_bf16 v[38:41], v[204:207], v[180:183], v[38:41]
	v_mfma_f32_16x16x32_bf16 v[34:37], v[220:223], v[180:183], v[34:37]
	v_mfma_f32_16x16x32_bf16 v[22:25], v[204:207], v[188:191], v[22:25]
	v_mfma_f32_16x16x32_bf16 v[18:21], v[220:223], v[188:191], v[18:21]
	v_mfma_f32_16x16x32_bf16 v[6:9], v[204:207], v[196:199], v[6:9]
	v_mfma_f32_16x16x32_bf16 v[2:5], v[220:223], v[196:199], v[2:5]
	s_add_i32 s78, s78, 2
	s_add_u32 s22, s22, 0x100
	s_addc_u32 s23, s23, 0
	s_cmpk_gt_u32 s78, 0x53
	s_barrier
	s_cbranch_scc0 .LBB0_1084
	s_add_u32 s22, s42, 0xffffff00
	s_addc_u32 s23, s43, -1
	s_and_b64 vcc, exec, s[38:39]
	s_cbranch_vccnz .LBB0_1071
	v_mov_b32_e32 v2, 0
	s_mov_b32 s14, s75
	s_mov_b32 s50, s76
	s_mov_b64 s[6:7], s[12:13]
	s_mov_b32 s69, s77
	v_mov_b32_e32 v3, v2
	v_mov_b32_e32 v4, v2
	v_mov_b32_e32 v5, v2
	v_mov_b32_e32 v6, v2
	v_mov_b32_e32 v7, v2
	v_mov_b32_e32 v8, v2
	v_mov_b32_e32 v9, v2
	v_mov_b32_e32 v18, v2
	v_mov_b32_e32 v19, v2
	v_mov_b32_e32 v20, v2
	v_mov_b32_e32 v21, v2
	v_mov_b32_e32 v22, v2
	v_mov_b32_e32 v23, v2
	v_mov_b32_e32 v24, v2
	v_mov_b32_e32 v25, v2
	v_mov_b32_e32 v34, v2
	v_mov_b32_e32 v35, v2
	v_mov_b32_e32 v36, v2
	v_mov_b32_e32 v37, v2
	v_mov_b32_e32 v38, v2
	v_mov_b32_e32 v39, v2
	v_mov_b32_e32 v40, v2
	v_mov_b32_e32 v41, v2
	v_mov_b32_e32 v50, v2
	v_mov_b32_e32 v51, v2
	v_mov_b32_e32 v52, v2
	v_mov_b32_e32 v53, v2
	v_mov_b32_e32 v54, v2
	v_mov_b32_e32 v55, v2
	v_mov_b32_e32 v56, v2
	v_mov_b32_e32 v57, v2
	v_mov_b32_e32 v10, v2
	v_mov_b32_e32 v11, v2
	v_mov_b32_e32 v12, v2
	v_mov_b32_e32 v13, v2
	v_mov_b32_e32 v14, v2
	v_mov_b32_e32 v15, v2
	v_mov_b32_e32 v16, v2
	v_mov_b32_e32 v17, v2
	v_mov_b32_e32 v26, v2
	v_mov_b32_e32 v27, v2
	v_mov_b32_e32 v28, v2
	v_mov_b32_e32 v29, v2
	v_mov_b32_e32 v30, v2
	v_mov_b32_e32 v31, v2
	v_mov_b32_e32 v32, v2
	v_mov_b32_e32 v33, v2
	v_mov_b32_e32 v42, v2
	v_mov_b32_e32 v43, v2
	v_mov_b32_e32 v44, v2
	v_mov_b32_e32 v45, v2
	v_mov_b32_e32 v46, v2
	v_mov_b32_e32 v47, v2
	v_mov_b32_e32 v48, v2
	v_mov_b32_e32 v49, v2
	v_mov_b32_e32 v58, v2
	v_mov_b32_e32 v59, v2
	v_mov_b32_e32 v60, v2
	v_mov_b32_e32 v61, v2
	v_mov_b32_e32 v62, v2
	v_mov_b32_e32 v63, v2
	v_mov_b32_e32 v64, v2
	v_mov_b32_e32 v65, v2
	v_mov_b32_e32 v66, v2
	v_mov_b32_e32 v67, v2
	v_mov_b32_e32 v68, v2
	v_mov_b32_e32 v69, v2
	v_mov_b32_e32 v70, v2
	v_mov_b32_e32 v71, v2
	v_mov_b32_e32 v72, v2
	v_mov_b32_e32 v73, v2
	v_mov_b32_e32 v82, v2
	v_mov_b32_e32 v83, v2
	v_mov_b32_e32 v84, v2
	v_mov_b32_e32 v85, v2
	v_mov_b32_e32 v86, v2
	v_mov_b32_e32 v87, v2
	v_mov_b32_e32 v88, v2
	v_mov_b32_e32 v89, v2
	v_mov_b32_e32 v98, v2
	v_mov_b32_e32 v99, v2
	v_mov_b32_e32 v100, v2
	v_mov_b32_e32 v101, v2
	v_mov_b32_e32 v102, v2
	v_mov_b32_e32 v103, v2
	v_mov_b32_e32 v104, v2
	v_mov_b32_e32 v105, v2
	v_mov_b32_e32 v114, v2
	v_mov_b32_e32 v115, v2
	v_mov_b32_e32 v116, v2
	v_mov_b32_e32 v117, v2
	v_mov_b32_e32 v118, v2
	v_mov_b32_e32 v119, v2
	v_mov_b32_e32 v120, v2
	v_mov_b32_e32 v121, v2
	v_mov_b32_e32 v74, v2
	v_mov_b32_e32 v75, v2
	v_mov_b32_e32 v76, v2
	v_mov_b32_e32 v77, v2
	v_mov_b32_e32 v78, v2
	v_mov_b32_e32 v79, v2
	v_mov_b32_e32 v80, v2
	v_mov_b32_e32 v81, v2
	v_mov_b32_e32 v90, v2
	v_mov_b32_e32 v91, v2
	v_mov_b32_e32 v92, v2
	v_mov_b32_e32 v93, v2
	v_mov_b32_e32 v94, v2
	v_mov_b32_e32 v95, v2
	v_mov_b32_e32 v96, v2
	v_mov_b32_e32 v97, v2
	v_mov_b32_e32 v106, v2
	v_mov_b32_e32 v107, v2
	v_mov_b32_e32 v108, v2
	v_mov_b32_e32 v109, v2
	v_mov_b32_e32 v110, v2
	v_mov_b32_e32 v111, v2
	v_mov_b32_e32 v112, v2
	v_mov_b32_e32 v113, v2
	v_mov_b32_e32 v122, v2
	v_mov_b32_e32 v123, v2
	v_mov_b32_e32 v124, v2
	v_mov_b32_e32 v125, v2
	v_mov_b32_e32 v126, v2
	v_mov_b32_e32 v127, v2
	v_mov_b32_e32 v128, v2
	v_mov_b32_e32 v129, v2
	s_andn2_b64 vcc, exec, s[0:1]
	s_cbranch_vccnz .LBB0_1072
